# norm fast-path stores write-through (sc1); L2 writeback skipped after those norm phases when the grid has 256 workgroups
# baseline (speedup 1.0000x reference)
.LBB0_584:
	s_ashr_i32 s17, s20, 6
	s_add_i32 s17, s17, s92
	v_readlane_b32 s18, v249, 49
	s_mul_i32 s19, s18, s17
	s_add_i32 s18, s19, s18
	s_min_i32 s23, s19, 0x4000
	s_cmp_lt_i32 s18, s23
	s_cbranch_scc1 .LBB0_605
	s_min_i32 s22, s18, 0x4000
	s_and_b64 s[6:7], s[6:7], exec
	s_movk_i32 s6, 0xc00
	s_cselect_b32 s18, s6, 0x1800
	s_and_b64 s[6:7], s[28:29], exec
	s_cselect_b32 s6, 0x2d000, 0
	s_waitcnt lgkmcnt(0)
	s_add_u32 s6, s8, s6
	s_addc_u32 s7, s9, 0
	s_and_b64 s[4:5], s[4:5], exec
	s_cselect_b32 s4, 0, s18
	s_lshl_b32 s4, s4, 2
	s_add_u32 s18, s6, s4
	s_addc_u32 s19, s7, 0
	s_and_b64 s[4:5], s[28:29], exec
	s_cselect_b32 s4, 0x1000, 0
	s_cmp_eq_u32 s3, 17
	s_movk_i32 s5, 0x4400
	s_cselect_b32 s24, 0x4000, s5
	s_add_i32 s6, s24, 0xffffc000
	s_add_u32 s14, s14, s4
	s_addc_u32 s15, s15, 0
	s_add_i32 s25, s17, 0x4000
	v_lshlrev_b32_e32 v0, 2, v2
	s_cmp_lg_u64 s[10:11], 0
	v_and_b32_e32 v3, 0xfc, v0
	s_cselect_b64 s[4:5], -1, 0
	s_cmp_lg_u32 s16, 0
	v_lshlrev_b32_e32 v0, 1, v3
	s_cselect_b64 s[20:21], -1, 0
	s_cmp_lt_i32 s17, s6
	v_lshl_add_u64 v[4:5], s[8:9], 0, v[0:1]
	v_lshl_add_u64 v[58:59], s[12:13], 0, v[0:1]
	v_and_b32_e32 v0, 63, v2
	s_cselect_b64 s[6:7], -1, 0
	s_mov_b64 s[8:9], 0x9000000
	s_and_b32 s26, s16, 3
	v_lshlrev_b32_e32 v0, 3, v0
	v_lshl_add_u64 v[50:51], v[4:5], 0, s[8:9]
	v_lshlrev_b32_e32 v6, 2, v3
	v_mov_b32_e32 v7, v1
	s_mov_b64 s[8:9], 0x4c00000
	s_cmp_gt_u32 s16, 3
	v_lshl_add_u64 v[2:3], s[12:13], 0, v[0:1]
	s_mov_b64 s[12:13], 0x400
	v_lshl_add_u64 v[52:53], s[14:15], 0, v[6:7]
	v_lshl_add_u64 v[54:55], v[4:5], 0, s[8:9]
	v_lshl_add_u64 v[56:57], s[10:11], 0, v[6:7]
	s_cselect_b64 s[8:9], -1, 0
	s_cmp_lg_u32 s26, 0
	v_lshl_add_u64 v[60:61], s[18:19], 0, v[6:7]
	s_mov_b64 s[14:15], 0x1000
	v_lshl_add_u64 v[64:65], v[2:3], 0, s[12:13]
	v_mov_b32_e32 v2, v1
	v_mov_b32_e32 v3, v1
	v_mov_b32_e32 v4, v1
	v_mov_b32_e32 v5, v1
	v_mov_b32_e32 v6, v1
	v_mov_b32_e32 v8, v1
	v_mov_b32_e32 v9, v1
	v_mov_b32_e32 v10, v1
	v_mov_b32_e32 v11, v1
	v_mov_b32_e32 v12, v1
	v_mov_b32_e32 v13, v1
	v_mov_b32_e32 v14, v1
	v_mov_b32_e32 v15, v1
	s_cselect_b64 s[10:11], -1, 0
	v_lshl_add_u64 v[62:63], v[60:61], 0, s[14:15]
	s_lshl_b32 s14, s16, 21
	v_mov_b32_e32 v0, v1
	v_mov_b64_e32 v[16:17], v[14:15]
	s_and_b32 s27, s14, 0x1800000
	s_mov_b32 s28, -1
	s_xor_b64 s[12:13], s[20:21], -1
	v_mov_b64_e32 v[14:15], v[12:13]
	v_mov_b64_e32 v[12:13], v[10:11]
	v_mov_b64_e32 v[10:11], v[8:9]
	v_mov_b64_e32 v[8:9], v[6:7]
	v_mov_b64_e32 v[6:7], v[4:5]
	v_mov_b64_e32 v[4:5], v[2:3]
	v_mov_b64_e32 v[2:3], v[0:1]
	s_and_b64 vcc, exec, s[4:5]
	s_cbranch_vccnz .Lnf_skip
	s_sub_i32 vcc_lo, s22, s23
	s_cmp_lg_u32 vcc_lo, 8
	s_cbranch_scc1 .Lnf_skip
	s_lshr_b32 vcc_lo, s23, 12
	s_add_i32 vcc_hi, s22, -1
	s_lshr_b32 vcc_hi, vcc_hi, 12
	s_cmp_lg_u32 vcc_lo, vcc_hi
	s_cbranch_scc1 .Lnf_skip
	s_mul_i32 vcc_lo, vcc_lo, 0x9000
	s_mov_b32 vcc_hi, 0
	v_and_b32_e32 v114, 63, v224
	v_mov_b32_e32 v115, 0
	v_mov_b32_e32 v117, 0
	v_lshlrev_b32_e32 v116, 4, v114
	v_lshlrev_b32_e32 v114, 3, v114
	v_lshl_add_u64 v[118:119], v[52:53], 0, v[116:117]
	v_lshl_add_u64 v[120:121], v[62:63], 0, v[116:117]
	v_lshl_add_u64 v[194:195], v[60:61], 0, v[116:117]
	v_lshl_add_u64 v[120:121], v[120:121], 0, vcc
	v_lshl_add_u64 v[194:195], v[194:195], 0, vcc
	global_load_dwordx4 v[66:69], v[118:119], off
	global_load_dwordx4 v[70:73], v[118:119], off offset:16
	global_load_dwordx4 v[74:77], v[118:119], off offset:2048
	global_load_dwordx4 v[78:81], v[118:119], off offset:2064
	global_load_dwordx4 v[82:85], v[120:121], off
	global_load_dwordx4 v[86:89], v[120:121], off offset:16
	global_load_dwordx4 v[90:93], v[120:121], off offset:2048
	global_load_dwordx4 v[94:97], v[120:121], off offset:2064
	global_load_dwordx4 v[98:101], v[194:195], off
	global_load_dwordx4 v[102:105], v[194:195], off offset:16
	global_load_dwordx4 v[106:109], v[194:195], off offset:2048
	global_load_dwordx4 v[110:113], v[194:195], off offset:2064
	s_mov_b32 vcc_lo, s23
	s_lshl_b64 vcc, vcc, 11
	v_lshl_add_u64 v[186:187], v[54:55], 0, v[114:115]
	v_lshl_add_u64 v[186:187], v[186:187], 0, vcc
	s_mov_b64 vcc, 0x1000
	v_lshl_add_u64 v[188:189], v[186:187], 0, vcc
	v_lshl_add_u64 v[190:191], v[188:189], 0, vcc
	v_lshl_add_u64 v[192:193], v[190:191], 0, vcc
	global_load_dwordx4 v[122:125], v[186:187], off
	global_load_dwordx4 v[126:129], v[186:187], off offset:1024
	global_load_dwordx4 v[130:133], v[186:187], off offset:2048
	global_load_dwordx4 v[134:137], v[186:187], off offset:3072
	global_load_dwordx4 v[138:141], v[188:189], off
	global_load_dwordx4 v[142:145], v[188:189], off offset:1024
	global_load_dwordx4 v[146:149], v[188:189], off offset:2048
	global_load_dwordx4 v[150:153], v[188:189], off offset:3072
	global_load_dwordx4 v[154:157], v[190:191], off
	global_load_dwordx4 v[158:161], v[190:191], off offset:1024
	global_load_dwordx4 v[162:165], v[190:191], off offset:2048
	global_load_dwordx4 v[166:169], v[190:191], off offset:3072
	global_load_dwordx4 v[170:173], v[192:193], off
	global_load_dwordx4 v[174:177], v[192:193], off offset:1024
	global_load_dwordx4 v[178:181], v[192:193], off offset:2048
	global_load_dwordx4 v[182:185], v[192:193], off offset:3072
	v_mov_b32_e32 v220, 0x3a800000
	v_mov_b32_e32 v221, 0x358637bd
	s_mov_b64 vcc, 0x4400000
	v_lshl_add_u64 v[186:187], v[186:187], 0, vcc
	v_lshl_add_u64 v[188:189], v[188:189], 0, vcc
	v_lshl_add_u64 v[190:191], v[190:191], 0, vcc
	v_lshl_add_u64 v[192:193], v[192:193], 0, vcc
	s_waitcnt vmcnt(16)
	v_pk_add_f32 v[82:83], v[82:83], 1.0 op_sel_hi:[1,0]
	v_pk_add_f32 v[84:85], v[84:85], 1.0 op_sel_hi:[1,0]
	v_pk_add_f32 v[86:87], v[86:87], 1.0 op_sel_hi:[1,0]
	v_pk_add_f32 v[88:89], v[88:89], 1.0 op_sel_hi:[1,0]
	v_pk_add_f32 v[90:91], v[90:91], 1.0 op_sel_hi:[1,0]
	v_pk_add_f32 v[92:93], v[92:93], 1.0 op_sel_hi:[1,0]
	v_pk_add_f32 v[94:95], v[94:95], 1.0 op_sel_hi:[1,0]
	v_pk_add_f32 v[96:97], v[96:97], 1.0 op_sel_hi:[1,0]
	v_pk_mul_f32 v[66:67], v[66:67], v[82:83]
	v_pk_mul_f32 v[68:69], v[68:69], v[84:85]
	v_pk_mul_f32 v[70:71], v[70:71], v[86:87]
	v_pk_mul_f32 v[72:73], v[72:73], v[88:89]
	v_pk_mul_f32 v[74:75], v[74:75], v[90:91]
	v_pk_mul_f32 v[76:77], v[76:77], v[92:93]
	v_pk_mul_f32 v[78:79], v[78:79], v[94:95]
	v_pk_mul_f32 v[80:81], v[80:81], v[96:97]
	s_waitcnt vmcnt(14)
	v_lshlrev_b32_e32 v212, 16, v122
	v_and_b32_e32 v213, 0xffff0000, v122
	v_mul_f32_e32 v82, v212, v212
	v_mul_f32_e32 v83, v213, v213
	v_lshlrev_b32_e32 v214, 16, v123
	v_and_b32_e32 v215, 0xffff0000, v123
	v_fmac_f32_e32 v82, v214, v214
	v_fmac_f32_e32 v83, v215, v215
	v_lshlrev_b32_e32 v216, 16, v124
	v_and_b32_e32 v217, 0xffff0000, v124
	v_fmac_f32_e32 v82, v216, v216
	v_fmac_f32_e32 v83, v217, v217
	v_lshlrev_b32_e32 v218, 16, v125
	v_and_b32_e32 v219, 0xffff0000, v125
	v_fmac_f32_e32 v82, v218, v218
	v_fmac_f32_e32 v83, v219, v219
	v_lshlrev_b32_e32 v212, 16, v126
	v_and_b32_e32 v213, 0xffff0000, v126
	v_fmac_f32_e32 v82, v212, v212
	v_fmac_f32_e32 v83, v213, v213
	v_lshlrev_b32_e32 v214, 16, v127
	v_and_b32_e32 v215, 0xffff0000, v127
	v_fmac_f32_e32 v82, v214, v214
	v_fmac_f32_e32 v83, v215, v215
	v_lshlrev_b32_e32 v216, 16, v128
	v_and_b32_e32 v217, 0xffff0000, v128
	v_fmac_f32_e32 v82, v216, v216
	v_fmac_f32_e32 v83, v217, v217
	v_lshlrev_b32_e32 v218, 16, v129
	v_and_b32_e32 v219, 0xffff0000, v129
	v_fmac_f32_e32 v82, v218, v218
	v_fmac_f32_e32 v83, v219, v219
	s_waitcnt vmcnt(12)
	v_lshlrev_b32_e32 v212, 16, v130
	v_and_b32_e32 v213, 0xffff0000, v130
	v_mul_f32_e32 v84, v212, v212
	v_mul_f32_e32 v85, v213, v213
	v_lshlrev_b32_e32 v214, 16, v131
	v_and_b32_e32 v215, 0xffff0000, v131
	v_fmac_f32_e32 v84, v214, v214
	v_fmac_f32_e32 v85, v215, v215
	v_lshlrev_b32_e32 v216, 16, v132
	v_and_b32_e32 v217, 0xffff0000, v132
	v_fmac_f32_e32 v84, v216, v216
	v_fmac_f32_e32 v85, v217, v217
	v_lshlrev_b32_e32 v218, 16, v133
	v_and_b32_e32 v219, 0xffff0000, v133
	v_fmac_f32_e32 v84, v218, v218
	v_fmac_f32_e32 v85, v219, v219
	v_lshlrev_b32_e32 v212, 16, v134
	v_and_b32_e32 v213, 0xffff0000, v134
	v_fmac_f32_e32 v84, v212, v212
	v_fmac_f32_e32 v85, v213, v213
	v_lshlrev_b32_e32 v214, 16, v135
	v_and_b32_e32 v215, 0xffff0000, v135
	v_fmac_f32_e32 v84, v214, v214
	v_fmac_f32_e32 v85, v215, v215
	v_lshlrev_b32_e32 v216, 16, v136
	v_and_b32_e32 v217, 0xffff0000, v136
	v_fmac_f32_e32 v84, v216, v216
	v_fmac_f32_e32 v85, v217, v217
	v_lshlrev_b32_e32 v218, 16, v137
	v_and_b32_e32 v219, 0xffff0000, v137
	v_fmac_f32_e32 v84, v218, v218
	v_fmac_f32_e32 v85, v219, v219
	s_waitcnt vmcnt(10)
	v_lshlrev_b32_e32 v212, 16, v138
	v_and_b32_e32 v213, 0xffff0000, v138
	v_mul_f32_e32 v86, v212, v212
	v_mul_f32_e32 v87, v213, v213
	v_lshlrev_b32_e32 v214, 16, v139
	v_and_b32_e32 v215, 0xffff0000, v139
	v_fmac_f32_e32 v86, v214, v214
	v_fmac_f32_e32 v87, v215, v215
	v_lshlrev_b32_e32 v216, 16, v140
	v_and_b32_e32 v217, 0xffff0000, v140
	v_fmac_f32_e32 v86, v216, v216
	v_fmac_f32_e32 v87, v217, v217
	v_lshlrev_b32_e32 v218, 16, v141
	v_and_b32_e32 v219, 0xffff0000, v141
	v_fmac_f32_e32 v86, v218, v218
	v_fmac_f32_e32 v87, v219, v219
	v_lshlrev_b32_e32 v212, 16, v142
	v_and_b32_e32 v213, 0xffff0000, v142
	v_fmac_f32_e32 v86, v212, v212
	v_fmac_f32_e32 v87, v213, v213
	v_lshlrev_b32_e32 v214, 16, v143
	v_and_b32_e32 v215, 0xffff0000, v143
	v_fmac_f32_e32 v86, v214, v214
	v_fmac_f32_e32 v87, v215, v215
	v_lshlrev_b32_e32 v216, 16, v144
	v_and_b32_e32 v217, 0xffff0000, v144
	v_fmac_f32_e32 v86, v216, v216
	v_fmac_f32_e32 v87, v217, v217
	v_lshlrev_b32_e32 v218, 16, v145
	v_and_b32_e32 v219, 0xffff0000, v145
	v_fmac_f32_e32 v86, v218, v218
	v_fmac_f32_e32 v87, v219, v219
	s_waitcnt vmcnt(8)
	v_lshlrev_b32_e32 v212, 16, v146
	v_and_b32_e32 v213, 0xffff0000, v146
	v_mul_f32_e32 v88, v212, v212
	v_mul_f32_e32 v89, v213, v213
	v_lshlrev_b32_e32 v214, 16, v147
	v_and_b32_e32 v215, 0xffff0000, v147
	v_fmac_f32_e32 v88, v214, v214
	v_fmac_f32_e32 v89, v215, v215
	v_lshlrev_b32_e32 v216, 16, v148
	v_and_b32_e32 v217, 0xffff0000, v148
	v_fmac_f32_e32 v88, v216, v216
	v_fmac_f32_e32 v89, v217, v217
	v_lshlrev_b32_e32 v218, 16, v149
	v_and_b32_e32 v219, 0xffff0000, v149
	v_fmac_f32_e32 v88, v218, v218
	v_fmac_f32_e32 v89, v219, v219
	v_lshlrev_b32_e32 v212, 16, v150
	v_and_b32_e32 v213, 0xffff0000, v150
	v_fmac_f32_e32 v88, v212, v212
	v_fmac_f32_e32 v89, v213, v213
	v_lshlrev_b32_e32 v214, 16, v151
	v_and_b32_e32 v215, 0xffff0000, v151
	v_fmac_f32_e32 v88, v214, v214
	v_fmac_f32_e32 v89, v215, v215
	v_lshlrev_b32_e32 v216, 16, v152
	v_and_b32_e32 v217, 0xffff0000, v152
	v_fmac_f32_e32 v88, v216, v216
	v_fmac_f32_e32 v89, v217, v217
	v_lshlrev_b32_e32 v218, 16, v153
	v_and_b32_e32 v219, 0xffff0000, v153
	v_fmac_f32_e32 v88, v218, v218
	v_fmac_f32_e32 v89, v219, v219
	s_waitcnt vmcnt(6)
	v_lshlrev_b32_e32 v212, 16, v154
	v_and_b32_e32 v213, 0xffff0000, v154
	v_mul_f32_e32 v90, v212, v212
	v_mul_f32_e32 v91, v213, v213
	v_lshlrev_b32_e32 v214, 16, v155
	v_and_b32_e32 v215, 0xffff0000, v155
	v_fmac_f32_e32 v90, v214, v214
	v_fmac_f32_e32 v91, v215, v215
	v_lshlrev_b32_e32 v216, 16, v156
	v_and_b32_e32 v217, 0xffff0000, v156
	v_fmac_f32_e32 v90, v216, v216
	v_fmac_f32_e32 v91, v217, v217
	v_lshlrev_b32_e32 v218, 16, v157
	v_and_b32_e32 v219, 0xffff0000, v157
	v_fmac_f32_e32 v90, v218, v218
	v_fmac_f32_e32 v91, v219, v219
	v_lshlrev_b32_e32 v212, 16, v158
	v_and_b32_e32 v213, 0xffff0000, v158
	v_fmac_f32_e32 v90, v212, v212
	v_fmac_f32_e32 v91, v213, v213
	v_lshlrev_b32_e32 v214, 16, v159
	v_and_b32_e32 v215, 0xffff0000, v159
	v_fmac_f32_e32 v90, v214, v214
	v_fmac_f32_e32 v91, v215, v215
	v_lshlrev_b32_e32 v216, 16, v160
	v_and_b32_e32 v217, 0xffff0000, v160
	v_fmac_f32_e32 v90, v216, v216
	v_fmac_f32_e32 v91, v217, v217
	v_lshlrev_b32_e32 v218, 16, v161
	v_and_b32_e32 v219, 0xffff0000, v161
	v_fmac_f32_e32 v90, v218, v218
	v_fmac_f32_e32 v91, v219, v219
	s_waitcnt vmcnt(4)
	v_lshlrev_b32_e32 v212, 16, v162
	v_and_b32_e32 v213, 0xffff0000, v162
	v_mul_f32_e32 v92, v212, v212
	v_mul_f32_e32 v93, v213, v213
	v_lshlrev_b32_e32 v214, 16, v163
	v_and_b32_e32 v215, 0xffff0000, v163
	v_fmac_f32_e32 v92, v214, v214
	v_fmac_f32_e32 v93, v215, v215
	v_lshlrev_b32_e32 v216, 16, v164
	v_and_b32_e32 v217, 0xffff0000, v164
	v_fmac_f32_e32 v92, v216, v216
	v_fmac_f32_e32 v93, v217, v217
	v_lshlrev_b32_e32 v218, 16, v165
	v_and_b32_e32 v219, 0xffff0000, v165
	v_fmac_f32_e32 v92, v218, v218
	v_fmac_f32_e32 v93, v219, v219
	v_lshlrev_b32_e32 v212, 16, v166
	v_and_b32_e32 v213, 0xffff0000, v166
	v_fmac_f32_e32 v92, v212, v212
	v_fmac_f32_e32 v93, v213, v213
	v_lshlrev_b32_e32 v214, 16, v167
	v_and_b32_e32 v215, 0xffff0000, v167
	v_fmac_f32_e32 v92, v214, v214
	v_fmac_f32_e32 v93, v215, v215
	v_lshlrev_b32_e32 v216, 16, v168
	v_and_b32_e32 v217, 0xffff0000, v168
	v_fmac_f32_e32 v92, v216, v216
	v_fmac_f32_e32 v93, v217, v217
	v_lshlrev_b32_e32 v218, 16, v169
	v_and_b32_e32 v219, 0xffff0000, v169
	v_fmac_f32_e32 v92, v218, v218
	v_fmac_f32_e32 v93, v219, v219
	s_waitcnt vmcnt(2)
	v_lshlrev_b32_e32 v212, 16, v170
	v_and_b32_e32 v213, 0xffff0000, v170
	v_mul_f32_e32 v94, v212, v212
	v_mul_f32_e32 v95, v213, v213
	v_lshlrev_b32_e32 v214, 16, v171
	v_and_b32_e32 v215, 0xffff0000, v171
	v_fmac_f32_e32 v94, v214, v214
	v_fmac_f32_e32 v95, v215, v215
	v_lshlrev_b32_e32 v216, 16, v172
	v_and_b32_e32 v217, 0xffff0000, v172
	v_fmac_f32_e32 v94, v216, v216
	v_fmac_f32_e32 v95, v217, v217
	v_lshlrev_b32_e32 v218, 16, v173
	v_and_b32_e32 v219, 0xffff0000, v173
	v_fmac_f32_e32 v94, v218, v218
	v_fmac_f32_e32 v95, v219, v219
	v_lshlrev_b32_e32 v212, 16, v174
	v_and_b32_e32 v213, 0xffff0000, v174
	v_fmac_f32_e32 v94, v212, v212
	v_fmac_f32_e32 v95, v213, v213
	v_lshlrev_b32_e32 v214, 16, v175
	v_and_b32_e32 v215, 0xffff0000, v175
	v_fmac_f32_e32 v94, v214, v214
	v_fmac_f32_e32 v95, v215, v215
	v_lshlrev_b32_e32 v216, 16, v176
	v_and_b32_e32 v217, 0xffff0000, v176
	v_fmac_f32_e32 v94, v216, v216
	v_fmac_f32_e32 v95, v217, v217
	v_lshlrev_b32_e32 v218, 16, v177
	v_and_b32_e32 v219, 0xffff0000, v177
	v_fmac_f32_e32 v94, v218, v218
	v_fmac_f32_e32 v95, v219, v219
	s_waitcnt vmcnt(0)
	v_lshlrev_b32_e32 v212, 16, v178
	v_and_b32_e32 v213, 0xffff0000, v178
	v_mul_f32_e32 v96, v212, v212
	v_mul_f32_e32 v97, v213, v213
	v_lshlrev_b32_e32 v214, 16, v179
	v_and_b32_e32 v215, 0xffff0000, v179
	v_fmac_f32_e32 v96, v214, v214
	v_fmac_f32_e32 v97, v215, v215
	v_lshlrev_b32_e32 v216, 16, v180
	v_and_b32_e32 v217, 0xffff0000, v180
	v_fmac_f32_e32 v96, v216, v216
	v_fmac_f32_e32 v97, v217, v217
	v_lshlrev_b32_e32 v218, 16, v181
	v_and_b32_e32 v219, 0xffff0000, v181
	v_fmac_f32_e32 v96, v218, v218
	v_fmac_f32_e32 v97, v219, v219
	v_lshlrev_b32_e32 v212, 16, v182
	v_and_b32_e32 v213, 0xffff0000, v182
	v_fmac_f32_e32 v96, v212, v212
	v_fmac_f32_e32 v97, v213, v213
	v_lshlrev_b32_e32 v214, 16, v183
	v_and_b32_e32 v215, 0xffff0000, v183
	v_fmac_f32_e32 v96, v214, v214
	v_fmac_f32_e32 v97, v215, v215
	v_lshlrev_b32_e32 v216, 16, v184
	v_and_b32_e32 v217, 0xffff0000, v184
	v_fmac_f32_e32 v96, v216, v216
	v_fmac_f32_e32 v97, v217, v217
	v_lshlrev_b32_e32 v218, 16, v185
	v_and_b32_e32 v219, 0xffff0000, v185
	v_fmac_f32_e32 v96, v218, v218
	v_fmac_f32_e32 v97, v219, v219
	v_add_f32_e32 v82, v82, v83
	v_add_f32_e32 v84, v84, v85
	v_add_f32_e32 v86, v86, v87
	v_add_f32_e32 v88, v88, v89
	v_add_f32_e32 v90, v90, v91
	v_add_f32_e32 v92, v92, v93
	v_add_f32_e32 v94, v94, v95
	v_add_f32_e32 v96, v96, v97
	v_add_f32_dpp v82, v82, v82 quad_perm:[1,0,3,2] row_mask:0xf bank_mask:0xf
	v_add_f32_dpp v84, v84, v84 quad_perm:[1,0,3,2] row_mask:0xf bank_mask:0xf
	v_add_f32_dpp v86, v86, v86 quad_perm:[1,0,3,2] row_mask:0xf bank_mask:0xf
	v_add_f32_dpp v88, v88, v88 quad_perm:[1,0,3,2] row_mask:0xf bank_mask:0xf
	v_add_f32_dpp v90, v90, v90 quad_perm:[1,0,3,2] row_mask:0xf bank_mask:0xf
	v_add_f32_dpp v92, v92, v92 quad_perm:[1,0,3,2] row_mask:0xf bank_mask:0xf
	v_add_f32_dpp v94, v94, v94 quad_perm:[1,0,3,2] row_mask:0xf bank_mask:0xf
	v_add_f32_dpp v96, v96, v96 quad_perm:[1,0,3,2] row_mask:0xf bank_mask:0xf
	v_add_f32_dpp v82, v82, v82 quad_perm:[2,3,0,1] row_mask:0xf bank_mask:0xf
	v_add_f32_dpp v84, v84, v84 quad_perm:[2,3,0,1] row_mask:0xf bank_mask:0xf
	v_add_f32_dpp v86, v86, v86 quad_perm:[2,3,0,1] row_mask:0xf bank_mask:0xf
	v_add_f32_dpp v88, v88, v88 quad_perm:[2,3,0,1] row_mask:0xf bank_mask:0xf
	v_add_f32_dpp v90, v90, v90 quad_perm:[2,3,0,1] row_mask:0xf bank_mask:0xf
	v_add_f32_dpp v92, v92, v92 quad_perm:[2,3,0,1] row_mask:0xf bank_mask:0xf
	v_add_f32_dpp v94, v94, v94 quad_perm:[2,3,0,1] row_mask:0xf bank_mask:0xf
	v_add_f32_dpp v96, v96, v96 quad_perm:[2,3,0,1] row_mask:0xf bank_mask:0xf
	v_add_f32_dpp v82, v82, v82 row_half_mirror row_mask:0xf bank_mask:0xf
	v_add_f32_dpp v84, v84, v84 row_half_mirror row_mask:0xf bank_mask:0xf
	v_add_f32_dpp v86, v86, v86 row_half_mirror row_mask:0xf bank_mask:0xf
	v_add_f32_dpp v88, v88, v88 row_half_mirror row_mask:0xf bank_mask:0xf
	v_add_f32_dpp v90, v90, v90 row_half_mirror row_mask:0xf bank_mask:0xf
	v_add_f32_dpp v92, v92, v92 row_half_mirror row_mask:0xf bank_mask:0xf
	v_add_f32_dpp v94, v94, v94 row_half_mirror row_mask:0xf bank_mask:0xf
	v_add_f32_dpp v96, v96, v96 row_half_mirror row_mask:0xf bank_mask:0xf
	v_add_f32_dpp v82, v82, v82 row_mirror row_mask:0xf bank_mask:0xf
	v_add_f32_dpp v84, v84, v84 row_mirror row_mask:0xf bank_mask:0xf
	v_add_f32_dpp v86, v86, v86 row_mirror row_mask:0xf bank_mask:0xf
	v_add_f32_dpp v88, v88, v88 row_mirror row_mask:0xf bank_mask:0xf
	v_add_f32_dpp v90, v90, v90 row_mirror row_mask:0xf bank_mask:0xf
	v_add_f32_dpp v92, v92, v92 row_mirror row_mask:0xf bank_mask:0xf
	v_add_f32_dpp v94, v94, v94 row_mirror row_mask:0xf bank_mask:0xf
	v_add_f32_dpp v96, v96, v96 row_mirror row_mask:0xf bank_mask:0xf
	v_add_f32_dpp v82, v82, v82 row_bcast:15 row_mask:0xa bank_mask:0xf
	v_add_f32_dpp v84, v84, v84 row_bcast:15 row_mask:0xa bank_mask:0xf
	v_add_f32_dpp v86, v86, v86 row_bcast:15 row_mask:0xa bank_mask:0xf
	v_add_f32_dpp v88, v88, v88 row_bcast:15 row_mask:0xa bank_mask:0xf
	v_add_f32_dpp v90, v90, v90 row_bcast:15 row_mask:0xa bank_mask:0xf
	v_add_f32_dpp v92, v92, v92 row_bcast:15 row_mask:0xa bank_mask:0xf
	v_add_f32_dpp v94, v94, v94 row_bcast:15 row_mask:0xa bank_mask:0xf
	v_add_f32_dpp v96, v96, v96 row_bcast:15 row_mask:0xa bank_mask:0xf
	v_add_f32_dpp v82, v82, v82 row_bcast:31 row_mask:0xc bank_mask:0xf
	v_add_f32_dpp v84, v84, v84 row_bcast:31 row_mask:0xc bank_mask:0xf
	v_add_f32_dpp v86, v86, v86 row_bcast:31 row_mask:0xc bank_mask:0xf
	v_add_f32_dpp v88, v88, v88 row_bcast:31 row_mask:0xc bank_mask:0xf
	v_add_f32_dpp v90, v90, v90 row_bcast:31 row_mask:0xc bank_mask:0xf
	v_add_f32_dpp v92, v92, v92 row_bcast:31 row_mask:0xc bank_mask:0xf
	v_add_f32_dpp v94, v94, v94 row_bcast:31 row_mask:0xc bank_mask:0xf
	v_add_f32_dpp v96, v96, v96 row_bcast:31 row_mask:0xc bank_mask:0xf
	v_readlane_b32 vcc_lo, v82, 63
	v_readlane_b32 vcc_hi, v84, 63
	s_nop 1
	v_fma_f32 v196, vcc_lo, v220, v221
	v_fma_f32 v198, vcc_hi, v220, v221
	s_nop 1
	v_readlane_b32 vcc_lo, v86, 63
	v_readlane_b32 vcc_hi, v88, 63
	s_nop 1
	v_fma_f32 v200, vcc_lo, v220, v221
	v_fma_f32 v202, vcc_hi, v220, v221
	s_nop 1
	v_readlane_b32 vcc_lo, v90, 63
	v_readlane_b32 vcc_hi, v92, 63
	s_nop 1
	v_fma_f32 v204, vcc_lo, v220, v221
	v_fma_f32 v206, vcc_hi, v220, v221
	s_nop 1
	v_readlane_b32 vcc_lo, v94, 63
	v_readlane_b32 vcc_hi, v96, 63
	s_nop 1
	v_fma_f32 v208, vcc_lo, v220, v221
	v_fma_f32 v210, vcc_hi, v220, v221
	s_nop 1
	v_rsq_f32_e32 v196, v196
	v_rsq_f32_e32 v198, v198
	v_rsq_f32_e32 v200, v200
	v_rsq_f32_e32 v202, v202
	v_rsq_f32_e32 v204, v204
	v_rsq_f32_e32 v206, v206
	v_rsq_f32_e32 v208, v208
	v_rsq_f32_e32 v210, v210
	s_nop 1
	v_lshlrev_b32_e32 v212, 16, v122
	v_and_b32_e32 v213, 0xffff0000, v122
	v_pk_mul_f32 v[212:213], v[212:213], v[196:197] op_sel_hi:[1,0]
	v_pk_fma_f32 v[212:213], v[212:213], v[66:67], v[98:99]
	v_cvt_pk_bf16_f32 v122, v212, v213
	v_lshlrev_b32_e32 v214, 16, v123
	v_and_b32_e32 v215, 0xffff0000, v123
	v_pk_mul_f32 v[214:215], v[214:215], v[196:197] op_sel_hi:[1,0]
	v_pk_fma_f32 v[214:215], v[214:215], v[68:69], v[100:101]
	v_cvt_pk_bf16_f32 v123, v214, v215
	v_lshlrev_b32_e32 v216, 16, v124
	v_and_b32_e32 v217, 0xffff0000, v124
	v_pk_mul_f32 v[216:217], v[216:217], v[196:197] op_sel_hi:[1,0]
	v_pk_fma_f32 v[216:217], v[216:217], v[70:71], v[102:103]
	v_cvt_pk_bf16_f32 v124, v216, v217
	v_lshlrev_b32_e32 v218, 16, v125
	v_and_b32_e32 v219, 0xffff0000, v125
	v_pk_mul_f32 v[218:219], v[218:219], v[196:197] op_sel_hi:[1,0]
	v_pk_fma_f32 v[218:219], v[218:219], v[72:73], v[104:105]
	v_cvt_pk_bf16_f32 v125, v218, v219
	v_lshlrev_b32_e32 v212, 16, v126
	v_and_b32_e32 v213, 0xffff0000, v126
	v_pk_mul_f32 v[212:213], v[212:213], v[196:197] op_sel_hi:[1,0]
	v_pk_fma_f32 v[212:213], v[212:213], v[74:75], v[106:107]
	v_cvt_pk_bf16_f32 v126, v212, v213
	v_lshlrev_b32_e32 v214, 16, v127
	v_and_b32_e32 v215, 0xffff0000, v127
	v_pk_mul_f32 v[214:215], v[214:215], v[196:197] op_sel_hi:[1,0]
	v_pk_fma_f32 v[214:215], v[214:215], v[76:77], v[108:109]
	v_cvt_pk_bf16_f32 v127, v214, v215
	v_lshlrev_b32_e32 v216, 16, v128
	v_and_b32_e32 v217, 0xffff0000, v128
	v_pk_mul_f32 v[216:217], v[216:217], v[196:197] op_sel_hi:[1,0]
	v_pk_fma_f32 v[216:217], v[216:217], v[78:79], v[110:111]
	v_cvt_pk_bf16_f32 v128, v216, v217
	v_lshlrev_b32_e32 v218, 16, v129
	v_and_b32_e32 v219, 0xffff0000, v129
	v_pk_mul_f32 v[218:219], v[218:219], v[196:197] op_sel_hi:[1,0]
	v_pk_fma_f32 v[218:219], v[218:219], v[80:81], v[112:113]
	v_cvt_pk_bf16_f32 v129, v218, v219
	global_store_dwordx4 v[186:187], v[122:125], off sc1
	global_store_dwordx4 v[186:187], v[126:129], off offset:1024 sc1
	v_lshlrev_b32_e32 v212, 16, v130
	v_and_b32_e32 v213, 0xffff0000, v130
	v_pk_mul_f32 v[212:213], v[212:213], v[198:199] op_sel_hi:[1,0]
	v_pk_fma_f32 v[212:213], v[212:213], v[66:67], v[98:99]
	v_cvt_pk_bf16_f32 v130, v212, v213
	v_lshlrev_b32_e32 v214, 16, v131
	v_and_b32_e32 v215, 0xffff0000, v131
	v_pk_mul_f32 v[214:215], v[214:215], v[198:199] op_sel_hi:[1,0]
	v_pk_fma_f32 v[214:215], v[214:215], v[68:69], v[100:101]
	v_cvt_pk_bf16_f32 v131, v214, v215
	v_lshlrev_b32_e32 v216, 16, v132
	v_and_b32_e32 v217, 0xffff0000, v132
	v_pk_mul_f32 v[216:217], v[216:217], v[198:199] op_sel_hi:[1,0]
	v_pk_fma_f32 v[216:217], v[216:217], v[70:71], v[102:103]
	v_cvt_pk_bf16_f32 v132, v216, v217
	v_lshlrev_b32_e32 v218, 16, v133
	v_and_b32_e32 v219, 0xffff0000, v133
	v_pk_mul_f32 v[218:219], v[218:219], v[198:199] op_sel_hi:[1,0]
	v_pk_fma_f32 v[218:219], v[218:219], v[72:73], v[104:105]
	v_cvt_pk_bf16_f32 v133, v218, v219
	v_lshlrev_b32_e32 v212, 16, v134
	v_and_b32_e32 v213, 0xffff0000, v134
	v_pk_mul_f32 v[212:213], v[212:213], v[198:199] op_sel_hi:[1,0]
	v_pk_fma_f32 v[212:213], v[212:213], v[74:75], v[106:107]
	v_cvt_pk_bf16_f32 v134, v212, v213
	v_lshlrev_b32_e32 v214, 16, v135
	v_and_b32_e32 v215, 0xffff0000, v135
	v_pk_mul_f32 v[214:215], v[214:215], v[198:199] op_sel_hi:[1,0]
	v_pk_fma_f32 v[214:215], v[214:215], v[76:77], v[108:109]
	v_cvt_pk_bf16_f32 v135, v214, v215
	v_lshlrev_b32_e32 v216, 16, v136
	v_and_b32_e32 v217, 0xffff0000, v136
	v_pk_mul_f32 v[216:217], v[216:217], v[198:199] op_sel_hi:[1,0]
	v_pk_fma_f32 v[216:217], v[216:217], v[78:79], v[110:111]
	v_cvt_pk_bf16_f32 v136, v216, v217
	v_lshlrev_b32_e32 v218, 16, v137
	v_and_b32_e32 v219, 0xffff0000, v137
	v_pk_mul_f32 v[218:219], v[218:219], v[198:199] op_sel_hi:[1,0]
	v_pk_fma_f32 v[218:219], v[218:219], v[80:81], v[112:113]
	v_cvt_pk_bf16_f32 v137, v218, v219
	global_store_dwordx4 v[186:187], v[130:133], off offset:2048 sc1
	global_store_dwordx4 v[186:187], v[134:137], off offset:3072 sc1
	v_lshlrev_b32_e32 v212, 16, v138
	v_and_b32_e32 v213, 0xffff0000, v138
	v_pk_mul_f32 v[212:213], v[212:213], v[200:201] op_sel_hi:[1,0]
	v_pk_fma_f32 v[212:213], v[212:213], v[66:67], v[98:99]
	v_cvt_pk_bf16_f32 v138, v212, v213
	v_lshlrev_b32_e32 v214, 16, v139
	v_and_b32_e32 v215, 0xffff0000, v139
	v_pk_mul_f32 v[214:215], v[214:215], v[200:201] op_sel_hi:[1,0]
	v_pk_fma_f32 v[214:215], v[214:215], v[68:69], v[100:101]
	v_cvt_pk_bf16_f32 v139, v214, v215
	v_lshlrev_b32_e32 v216, 16, v140
	v_and_b32_e32 v217, 0xffff0000, v140
	v_pk_mul_f32 v[216:217], v[216:217], v[200:201] op_sel_hi:[1,0]
	v_pk_fma_f32 v[216:217], v[216:217], v[70:71], v[102:103]
	v_cvt_pk_bf16_f32 v140, v216, v217
	v_lshlrev_b32_e32 v218, 16, v141
	v_and_b32_e32 v219, 0xffff0000, v141
	v_pk_mul_f32 v[218:219], v[218:219], v[200:201] op_sel_hi:[1,0]
	v_pk_fma_f32 v[218:219], v[218:219], v[72:73], v[104:105]
	v_cvt_pk_bf16_f32 v141, v218, v219
	v_lshlrev_b32_e32 v212, 16, v142
	v_and_b32_e32 v213, 0xffff0000, v142
	v_pk_mul_f32 v[212:213], v[212:213], v[200:201] op_sel_hi:[1,0]
	v_pk_fma_f32 v[212:213], v[212:213], v[74:75], v[106:107]
	v_cvt_pk_bf16_f32 v142, v212, v213
	v_lshlrev_b32_e32 v214, 16, v143
	v_and_b32_e32 v215, 0xffff0000, v143
	v_pk_mul_f32 v[214:215], v[214:215], v[200:201] op_sel_hi:[1,0]
	v_pk_fma_f32 v[214:215], v[214:215], v[76:77], v[108:109]
	v_cvt_pk_bf16_f32 v143, v214, v215
	v_lshlrev_b32_e32 v216, 16, v144
	v_and_b32_e32 v217, 0xffff0000, v144
	v_pk_mul_f32 v[216:217], v[216:217], v[200:201] op_sel_hi:[1,0]
	v_pk_fma_f32 v[216:217], v[216:217], v[78:79], v[110:111]
	v_cvt_pk_bf16_f32 v144, v216, v217
	v_lshlrev_b32_e32 v218, 16, v145
	v_and_b32_e32 v219, 0xffff0000, v145
	v_pk_mul_f32 v[218:219], v[218:219], v[200:201] op_sel_hi:[1,0]
	v_pk_fma_f32 v[218:219], v[218:219], v[80:81], v[112:113]
	v_cvt_pk_bf16_f32 v145, v218, v219
	global_store_dwordx4 v[188:189], v[138:141], off sc1
	global_store_dwordx4 v[188:189], v[142:145], off offset:1024 sc1
	v_lshlrev_b32_e32 v212, 16, v146
	v_and_b32_e32 v213, 0xffff0000, v146
	v_pk_mul_f32 v[212:213], v[212:213], v[202:203] op_sel_hi:[1,0]
	v_pk_fma_f32 v[212:213], v[212:213], v[66:67], v[98:99]
	v_cvt_pk_bf16_f32 v146, v212, v213
	v_lshlrev_b32_e32 v214, 16, v147
	v_and_b32_e32 v215, 0xffff0000, v147
	v_pk_mul_f32 v[214:215], v[214:215], v[202:203] op_sel_hi:[1,0]
	v_pk_fma_f32 v[214:215], v[214:215], v[68:69], v[100:101]
	v_cvt_pk_bf16_f32 v147, v214, v215
	v_lshlrev_b32_e32 v216, 16, v148
	v_and_b32_e32 v217, 0xffff0000, v148
	v_pk_mul_f32 v[216:217], v[216:217], v[202:203] op_sel_hi:[1,0]
	v_pk_fma_f32 v[216:217], v[216:217], v[70:71], v[102:103]
	v_cvt_pk_bf16_f32 v148, v216, v217
	v_lshlrev_b32_e32 v218, 16, v149
	v_and_b32_e32 v219, 0xffff0000, v149
	v_pk_mul_f32 v[218:219], v[218:219], v[202:203] op_sel_hi:[1,0]
	v_pk_fma_f32 v[218:219], v[218:219], v[72:73], v[104:105]
	v_cvt_pk_bf16_f32 v149, v218, v219
	v_lshlrev_b32_e32 v212, 16, v150
	v_and_b32_e32 v213, 0xffff0000, v150
	v_pk_mul_f32 v[212:213], v[212:213], v[202:203] op_sel_hi:[1,0]
	v_pk_fma_f32 v[212:213], v[212:213], v[74:75], v[106:107]
	v_cvt_pk_bf16_f32 v150, v212, v213
	v_lshlrev_b32_e32 v214, 16, v151
	v_and_b32_e32 v215, 0xffff0000, v151
	v_pk_mul_f32 v[214:215], v[214:215], v[202:203] op_sel_hi:[1,0]
	v_pk_fma_f32 v[214:215], v[214:215], v[76:77], v[108:109]
	v_cvt_pk_bf16_f32 v151, v214, v215
	v_lshlrev_b32_e32 v216, 16, v152
	v_and_b32_e32 v217, 0xffff0000, v152
	v_pk_mul_f32 v[216:217], v[216:217], v[202:203] op_sel_hi:[1,0]
	v_pk_fma_f32 v[216:217], v[216:217], v[78:79], v[110:111]
	v_cvt_pk_bf16_f32 v152, v216, v217
	v_lshlrev_b32_e32 v218, 16, v153
	v_and_b32_e32 v219, 0xffff0000, v153
	v_pk_mul_f32 v[218:219], v[218:219], v[202:203] op_sel_hi:[1,0]
	v_pk_fma_f32 v[218:219], v[218:219], v[80:81], v[112:113]
	v_cvt_pk_bf16_f32 v153, v218, v219
	global_store_dwordx4 v[188:189], v[146:149], off offset:2048 sc1
	global_store_dwordx4 v[188:189], v[150:153], off offset:3072 sc1
	v_lshlrev_b32_e32 v212, 16, v154
	v_and_b32_e32 v213, 0xffff0000, v154
	v_pk_mul_f32 v[212:213], v[212:213], v[204:205] op_sel_hi:[1,0]
	v_pk_fma_f32 v[212:213], v[212:213], v[66:67], v[98:99]
	v_cvt_pk_bf16_f32 v154, v212, v213
	v_lshlrev_b32_e32 v214, 16, v155
	v_and_b32_e32 v215, 0xffff0000, v155
	v_pk_mul_f32 v[214:215], v[214:215], v[204:205] op_sel_hi:[1,0]
	v_pk_fma_f32 v[214:215], v[214:215], v[68:69], v[100:101]
	v_cvt_pk_bf16_f32 v155, v214, v215
	v_lshlrev_b32_e32 v216, 16, v156
	v_and_b32_e32 v217, 0xffff0000, v156
	v_pk_mul_f32 v[216:217], v[216:217], v[204:205] op_sel_hi:[1,0]
	v_pk_fma_f32 v[216:217], v[216:217], v[70:71], v[102:103]
	v_cvt_pk_bf16_f32 v156, v216, v217
	v_lshlrev_b32_e32 v218, 16, v157
	v_and_b32_e32 v219, 0xffff0000, v157
	v_pk_mul_f32 v[218:219], v[218:219], v[204:205] op_sel_hi:[1,0]
	v_pk_fma_f32 v[218:219], v[218:219], v[72:73], v[104:105]
	v_cvt_pk_bf16_f32 v157, v218, v219
	v_lshlrev_b32_e32 v212, 16, v158
	v_and_b32_e32 v213, 0xffff0000, v158
	v_pk_mul_f32 v[212:213], v[212:213], v[204:205] op_sel_hi:[1,0]
	v_pk_fma_f32 v[212:213], v[212:213], v[74:75], v[106:107]
	v_cvt_pk_bf16_f32 v158, v212, v213
	v_lshlrev_b32_e32 v214, 16, v159
	v_and_b32_e32 v215, 0xffff0000, v159
	v_pk_mul_f32 v[214:215], v[214:215], v[204:205] op_sel_hi:[1,0]
	v_pk_fma_f32 v[214:215], v[214:215], v[76:77], v[108:109]
	v_cvt_pk_bf16_f32 v159, v214, v215
	v_lshlrev_b32_e32 v216, 16, v160
	v_and_b32_e32 v217, 0xffff0000, v160
	v_pk_mul_f32 v[216:217], v[216:217], v[204:205] op_sel_hi:[1,0]
	v_pk_fma_f32 v[216:217], v[216:217], v[78:79], v[110:111]
	v_cvt_pk_bf16_f32 v160, v216, v217
	v_lshlrev_b32_e32 v218, 16, v161
	v_and_b32_e32 v219, 0xffff0000, v161
	v_pk_mul_f32 v[218:219], v[218:219], v[204:205] op_sel_hi:[1,0]
	v_pk_fma_f32 v[218:219], v[218:219], v[80:81], v[112:113]
	v_cvt_pk_bf16_f32 v161, v218, v219
	global_store_dwordx4 v[190:191], v[154:157], off sc1
	global_store_dwordx4 v[190:191], v[158:161], off offset:1024 sc1
	v_lshlrev_b32_e32 v212, 16, v162
	v_and_b32_e32 v213, 0xffff0000, v162
	v_pk_mul_f32 v[212:213], v[212:213], v[206:207] op_sel_hi:[1,0]
	v_pk_fma_f32 v[212:213], v[212:213], v[66:67], v[98:99]
	v_cvt_pk_bf16_f32 v162, v212, v213
	v_lshlrev_b32_e32 v214, 16, v163
	v_and_b32_e32 v215, 0xffff0000, v163
	v_pk_mul_f32 v[214:215], v[214:215], v[206:207] op_sel_hi:[1,0]
	v_pk_fma_f32 v[214:215], v[214:215], v[68:69], v[100:101]
	v_cvt_pk_bf16_f32 v163, v214, v215
	v_lshlrev_b32_e32 v216, 16, v164
	v_and_b32_e32 v217, 0xffff0000, v164
	v_pk_mul_f32 v[216:217], v[216:217], v[206:207] op_sel_hi:[1,0]
	v_pk_fma_f32 v[216:217], v[216:217], v[70:71], v[102:103]
	v_cvt_pk_bf16_f32 v164, v216, v217
	v_lshlrev_b32_e32 v218, 16, v165
	v_and_b32_e32 v219, 0xffff0000, v165
	v_pk_mul_f32 v[218:219], v[218:219], v[206:207] op_sel_hi:[1,0]
	v_pk_fma_f32 v[218:219], v[218:219], v[72:73], v[104:105]
	v_cvt_pk_bf16_f32 v165, v218, v219
	v_lshlrev_b32_e32 v212, 16, v166
	v_and_b32_e32 v213, 0xffff0000, v166
	v_pk_mul_f32 v[212:213], v[212:213], v[206:207] op_sel_hi:[1,0]
	v_pk_fma_f32 v[212:213], v[212:213], v[74:75], v[106:107]
	v_cvt_pk_bf16_f32 v166, v212, v213
	v_lshlrev_b32_e32 v214, 16, v167
	v_and_b32_e32 v215, 0xffff0000, v167
	v_pk_mul_f32 v[214:215], v[214:215], v[206:207] op_sel_hi:[1,0]
	v_pk_fma_f32 v[214:215], v[214:215], v[76:77], v[108:109]
	v_cvt_pk_bf16_f32 v167, v214, v215
	v_lshlrev_b32_e32 v216, 16, v168
	v_and_b32_e32 v217, 0xffff0000, v168
	v_pk_mul_f32 v[216:217], v[216:217], v[206:207] op_sel_hi:[1,0]
	v_pk_fma_f32 v[216:217], v[216:217], v[78:79], v[110:111]
	v_cvt_pk_bf16_f32 v168, v216, v217
	v_lshlrev_b32_e32 v218, 16, v169
	v_and_b32_e32 v219, 0xffff0000, v169
	v_pk_mul_f32 v[218:219], v[218:219], v[206:207] op_sel_hi:[1,0]
	v_pk_fma_f32 v[218:219], v[218:219], v[80:81], v[112:113]
	v_cvt_pk_bf16_f32 v169, v218, v219
	global_store_dwordx4 v[190:191], v[162:165], off offset:2048 sc1
	global_store_dwordx4 v[190:191], v[166:169], off offset:3072 sc1
	v_lshlrev_b32_e32 v212, 16, v170
	v_and_b32_e32 v213, 0xffff0000, v170
	v_pk_mul_f32 v[212:213], v[212:213], v[208:209] op_sel_hi:[1,0]
	v_pk_fma_f32 v[212:213], v[212:213], v[66:67], v[98:99]
	v_cvt_pk_bf16_f32 v170, v212, v213
	v_lshlrev_b32_e32 v214, 16, v171
	v_and_b32_e32 v215, 0xffff0000, v171
	v_pk_mul_f32 v[214:215], v[214:215], v[208:209] op_sel_hi:[1,0]
	v_pk_fma_f32 v[214:215], v[214:215], v[68:69], v[100:101]
	v_cvt_pk_bf16_f32 v171, v214, v215
	v_lshlrev_b32_e32 v216, 16, v172
	v_and_b32_e32 v217, 0xffff0000, v172
	v_pk_mul_f32 v[216:217], v[216:217], v[208:209] op_sel_hi:[1,0]
	v_pk_fma_f32 v[216:217], v[216:217], v[70:71], v[102:103]
	v_cvt_pk_bf16_f32 v172, v216, v217
	v_lshlrev_b32_e32 v218, 16, v173
	v_and_b32_e32 v219, 0xffff0000, v173
	v_pk_mul_f32 v[218:219], v[218:219], v[208:209] op_sel_hi:[1,0]
	v_pk_fma_f32 v[218:219], v[218:219], v[72:73], v[104:105]
	v_cvt_pk_bf16_f32 v173, v218, v219
	v_lshlrev_b32_e32 v212, 16, v174
	v_and_b32_e32 v213, 0xffff0000, v174
	v_pk_mul_f32 v[212:213], v[212:213], v[208:209] op_sel_hi:[1,0]
	v_pk_fma_f32 v[212:213], v[212:213], v[74:75], v[106:107]
	v_cvt_pk_bf16_f32 v174, v212, v213
	v_lshlrev_b32_e32 v214, 16, v175
	v_and_b32_e32 v215, 0xffff0000, v175
	v_pk_mul_f32 v[214:215], v[214:215], v[208:209] op_sel_hi:[1,0]
	v_pk_fma_f32 v[214:215], v[214:215], v[76:77], v[108:109]
	v_cvt_pk_bf16_f32 v175, v214, v215
	v_lshlrev_b32_e32 v216, 16, v176
	v_and_b32_e32 v217, 0xffff0000, v176
	v_pk_mul_f32 v[216:217], v[216:217], v[208:209] op_sel_hi:[1,0]
	v_pk_fma_f32 v[216:217], v[216:217], v[78:79], v[110:111]
	v_cvt_pk_bf16_f32 v176, v216, v217
	v_lshlrev_b32_e32 v218, 16, v177
	v_and_b32_e32 v219, 0xffff0000, v177
	v_pk_mul_f32 v[218:219], v[218:219], v[208:209] op_sel_hi:[1,0]
	v_pk_fma_f32 v[218:219], v[218:219], v[80:81], v[112:113]
	v_cvt_pk_bf16_f32 v177, v218, v219
	global_store_dwordx4 v[192:193], v[170:173], off sc1
	global_store_dwordx4 v[192:193], v[174:177], off offset:1024 sc1
	v_lshlrev_b32_e32 v212, 16, v178
	v_and_b32_e32 v213, 0xffff0000, v178
	v_pk_mul_f32 v[212:213], v[212:213], v[210:211] op_sel_hi:[1,0]
	v_pk_fma_f32 v[212:213], v[212:213], v[66:67], v[98:99]
	v_cvt_pk_bf16_f32 v178, v212, v213
	v_lshlrev_b32_e32 v214, 16, v179
	v_and_b32_e32 v215, 0xffff0000, v179
	v_pk_mul_f32 v[214:215], v[214:215], v[210:211] op_sel_hi:[1,0]
	v_pk_fma_f32 v[214:215], v[214:215], v[68:69], v[100:101]
	v_cvt_pk_bf16_f32 v179, v214, v215
	v_lshlrev_b32_e32 v216, 16, v180
	v_and_b32_e32 v217, 0xffff0000, v180
	v_pk_mul_f32 v[216:217], v[216:217], v[210:211] op_sel_hi:[1,0]
	v_pk_fma_f32 v[216:217], v[216:217], v[70:71], v[102:103]
	v_cvt_pk_bf16_f32 v180, v216, v217
	v_lshlrev_b32_e32 v218, 16, v181
	v_and_b32_e32 v219, 0xffff0000, v181
	v_pk_mul_f32 v[218:219], v[218:219], v[210:211] op_sel_hi:[1,0]
	v_pk_fma_f32 v[218:219], v[218:219], v[72:73], v[104:105]
	v_cvt_pk_bf16_f32 v181, v218, v219
	v_lshlrev_b32_e32 v212, 16, v182
	v_and_b32_e32 v213, 0xffff0000, v182
	v_pk_mul_f32 v[212:213], v[212:213], v[210:211] op_sel_hi:[1,0]
	v_pk_fma_f32 v[212:213], v[212:213], v[74:75], v[106:107]
	v_cvt_pk_bf16_f32 v182, v212, v213
	v_lshlrev_b32_e32 v214, 16, v183
	v_and_b32_e32 v215, 0xffff0000, v183
	v_pk_mul_f32 v[214:215], v[214:215], v[210:211] op_sel_hi:[1,0]
	v_pk_fma_f32 v[214:215], v[214:215], v[76:77], v[108:109]
	v_cvt_pk_bf16_f32 v183, v214, v215
	v_lshlrev_b32_e32 v216, 16, v184
	v_and_b32_e32 v217, 0xffff0000, v184
	v_pk_mul_f32 v[216:217], v[216:217], v[210:211] op_sel_hi:[1,0]
	v_pk_fma_f32 v[216:217], v[216:217], v[78:79], v[110:111]
	v_cvt_pk_bf16_f32 v184, v216, v217
	v_lshlrev_b32_e32 v218, 16, v185
	v_and_b32_e32 v219, 0xffff0000, v185
	v_pk_mul_f32 v[218:219], v[218:219], v[210:211] op_sel_hi:[1,0]
	v_pk_fma_f32 v[218:219], v[218:219], v[80:81], v[112:113]
	v_cvt_pk_bf16_f32 v185, v218, v219
	global_store_dwordx4 v[192:193], v[178:181], off offset:2048 sc1
	global_store_dwordx4 v[192:193], v[182:185], off offset:3072 sc1
	s_mov_b32 s23, s22
.Lnf_skip:
	s_andn2_b64 vcc, exec, s[6:7]
	s_cbranch_vccnz .Lnc_skip
	s_add_i32 vcc_lo, s24, 0xffffc000
	s_cmp_lt_u32 s48, vcc_lo
	s_cbranch_scc1 .Lnc_skip
	v_and_b32_e32 v114, 63, v224
	v_mov_b32_e32 v115, 0
	v_mov_b32_e32 v117, 0
	v_lshlrev_b32_e32 v116, 4, v114
	v_lshlrev_b32_e32 v114, 3, v114
	s_cmp_eq_u32 s16, 11
	s_cbranch_scc1 .Lnc_11
	s_cmp_eq_u32 s16, 4
	s_cbranch_scc1 .Lnc_4
	s_cmp_eq_u32 s16, 0
	s_cbranch_scc0 .Lnc_skip
	s_mov_b64 vcc, 0x24000
	v_lshl_add_u64 v[118:119], v[62:63], 0, v[116:117]
	v_lshl_add_u64 v[120:121], v[60:61], 0, v[116:117]
	v_lshl_add_u64 v[118:119], v[118:119], 0, vcc
	v_lshl_add_u64 v[120:121], v[120:121], 0, vcc
	v_lshl_add_u64 v[218:219], v[52:53], 0, v[116:117]
	global_load_dwordx4 v[66:69], v[218:219], off
	global_load_dwordx4 v[70:73], v[218:219], off offset:16
	global_load_dwordx4 v[74:77], v[218:219], off offset:2048
	global_load_dwordx4 v[78:81], v[218:219], off offset:2064
	global_load_dwordx4 v[82:85], v[118:119], off
	global_load_dwordx4 v[86:89], v[118:119], off offset:16
	global_load_dwordx4 v[90:93], v[118:119], off offset:2048
	global_load_dwordx4 v[94:97], v[118:119], off offset:2064
	global_load_dwordx4 v[98:101], v[120:121], off
	global_load_dwordx4 v[102:105], v[120:121], off offset:16
	global_load_dwordx4 v[106:109], v[120:121], off offset:2048
	global_load_dwordx4 v[110:113], v[120:121], off offset:2064
	s_mov_b32 vcc_lo, s25
	s_mov_b32 vcc_hi, 0
	s_lshl_b64 vcc, vcc, 11
	v_lshl_add_u64 v[118:119], v[54:55], 0, v[114:115]
	v_lshl_add_u64 v[118:119], v[118:119], 0, vcc
	global_load_dwordx4 v[122:125], v[118:119], off
	global_load_dwordx4 v[126:129], v[118:119], off offset:1024
	v_mov_b32_e32 v220, 0x3a800000
	v_mov_b32_e32 v221, 0x358637bd
	s_waitcnt vmcnt(2)
	v_pk_add_f32 v[82:83], v[82:83], 1.0 op_sel_hi:[1,0]
	v_pk_add_f32 v[84:85], v[84:85], 1.0 op_sel_hi:[1,0]
	v_pk_add_f32 v[86:87], v[86:87], 1.0 op_sel_hi:[1,0]
	v_pk_add_f32 v[88:89], v[88:89], 1.0 op_sel_hi:[1,0]
	v_pk_add_f32 v[90:91], v[90:91], 1.0 op_sel_hi:[1,0]
	v_pk_add_f32 v[92:93], v[92:93], 1.0 op_sel_hi:[1,0]
	v_pk_add_f32 v[94:95], v[94:95], 1.0 op_sel_hi:[1,0]
	v_pk_add_f32 v[96:97], v[96:97], 1.0 op_sel_hi:[1,0]
	v_pk_mul_f32 v[66:67], v[66:67], v[82:83]
	v_pk_mul_f32 v[68:69], v[68:69], v[84:85]
	v_pk_mul_f32 v[70:71], v[70:71], v[86:87]
	v_pk_mul_f32 v[72:73], v[72:73], v[88:89]
	v_pk_mul_f32 v[74:75], v[74:75], v[90:91]
	v_pk_mul_f32 v[76:77], v[76:77], v[92:93]
	v_pk_mul_f32 v[78:79], v[78:79], v[94:95]
	v_pk_mul_f32 v[80:81], v[80:81], v[96:97]
	s_waitcnt vmcnt(0)
	v_lshlrev_b32_e32 v82, 16, v122
	v_and_b32_e32 v83, 0xffff0000, v122
	v_lshlrev_b32_e32 v84, 16, v123
	v_and_b32_e32 v85, 0xffff0000, v123
	v_lshlrev_b32_e32 v86, 16, v124
	v_and_b32_e32 v87, 0xffff0000, v124
	v_lshlrev_b32_e32 v88, 16, v125
	v_and_b32_e32 v89, 0xffff0000, v125
	v_lshlrev_b32_e32 v90, 16, v126
	v_and_b32_e32 v91, 0xffff0000, v126
	v_lshlrev_b32_e32 v92, 16, v127
	v_and_b32_e32 v93, 0xffff0000, v127
	v_lshlrev_b32_e32 v94, 16, v128
	v_and_b32_e32 v95, 0xffff0000, v128
	v_lshlrev_b32_e32 v96, 16, v129
	v_and_b32_e32 v97, 0xffff0000, v129
	v_mul_f32_e32 v218, v82, v82
	v_mul_f32_e32 v219, v83, v83
	v_fmac_f32_e32 v218, v84, v84
	v_fmac_f32_e32 v219, v85, v85
	v_fmac_f32_e32 v218, v86, v86
	v_fmac_f32_e32 v219, v87, v87
	v_fmac_f32_e32 v218, v88, v88
	v_fmac_f32_e32 v219, v89, v89
	v_fmac_f32_e32 v218, v90, v90
	v_fmac_f32_e32 v219, v91, v91
	v_fmac_f32_e32 v218, v92, v92
	v_fmac_f32_e32 v219, v93, v93
	v_fmac_f32_e32 v218, v94, v94
	v_fmac_f32_e32 v219, v95, v95
	v_fmac_f32_e32 v218, v96, v96
	v_fmac_f32_e32 v219, v97, v97
	v_add_f32_e32 v218, v218, v219
	s_nop 1
	v_add_f32_dpp v218, v218, v218 quad_perm:[1,0,3,2] row_mask:0xf bank_mask:0xf
	s_nop 1
	v_add_f32_dpp v218, v218, v218 quad_perm:[2,3,0,1] row_mask:0xf bank_mask:0xf
	s_nop 1
	v_add_f32_dpp v218, v218, v218 row_half_mirror row_mask:0xf bank_mask:0xf
	s_nop 1
	v_add_f32_dpp v218, v218, v218 row_mirror row_mask:0xf bank_mask:0xf
	s_nop 1
	v_add_f32_dpp v218, v218, v218 row_bcast:15 row_mask:0xa bank_mask:0xf
	s_nop 1
	v_add_f32_dpp v218, v218, v218 row_bcast:31 row_mask:0xc bank_mask:0xf
	s_nop 1
	v_readlane_b32 vcc_lo, v218, 63
	s_nop 2
	v_fma_f32 v222, vcc_lo, v220, v221
	v_rsq_f32_e32 v222, v222
	s_mov_b64 vcc, 0x4400000
	v_lshl_add_u64 v[118:119], v[118:119], 0, vcc
	v_pk_mul_f32 v[82:83], v[82:83], v[222:223] op_sel_hi:[1,0]
	v_pk_fma_f32 v[82:83], v[82:83], v[66:67], v[98:99]
	v_pk_mul_f32 v[84:85], v[84:85], v[222:223] op_sel_hi:[1,0]
	v_pk_fma_f32 v[84:85], v[84:85], v[68:69], v[100:101]
	v_pk_mul_f32 v[86:87], v[86:87], v[222:223] op_sel_hi:[1,0]
	v_pk_fma_f32 v[86:87], v[86:87], v[70:71], v[102:103]
	v_pk_mul_f32 v[88:89], v[88:89], v[222:223] op_sel_hi:[1,0]
	v_pk_fma_f32 v[88:89], v[88:89], v[72:73], v[104:105]
	v_pk_mul_f32 v[90:91], v[90:91], v[222:223] op_sel_hi:[1,0]
	v_pk_fma_f32 v[90:91], v[90:91], v[74:75], v[106:107]
	v_pk_mul_f32 v[92:93], v[92:93], v[222:223] op_sel_hi:[1,0]
	v_pk_fma_f32 v[92:93], v[92:93], v[76:77], v[108:109]
	v_pk_mul_f32 v[94:95], v[94:95], v[222:223] op_sel_hi:[1,0]
	v_pk_fma_f32 v[94:95], v[94:95], v[78:79], v[110:111]
	v_pk_mul_f32 v[96:97], v[96:97], v[222:223] op_sel_hi:[1,0]
	v_pk_fma_f32 v[96:97], v[96:97], v[80:81], v[112:113]
	v_cvt_pk_bf16_f32 v66, v82, v83
	v_cvt_pk_bf16_f32 v67, v84, v85
	v_cvt_pk_bf16_f32 v68, v86, v87
	v_cvt_pk_bf16_f32 v69, v88, v89
	v_cvt_pk_bf16_f32 v70, v90, v91
	v_cvt_pk_bf16_f32 v71, v92, v93
	v_cvt_pk_bf16_f32 v72, v94, v95
	v_cvt_pk_bf16_f32 v73, v96, v97
	global_store_dwordx4 v[118:119], v[66:69], off sc1
	global_store_dwordx4 v[118:119], v[70:73], off offset:1024 sc1
	s_branch .Lnc_done
.Lnc_4:
	s_mov_b64 vcc, 0x24000
	v_lshl_add_u64 v[118:119], v[62:63], 0, v[116:117]
	v_lshl_add_u64 v[120:121], v[60:61], 0, v[116:117]
	v_lshl_add_u64 v[118:119], v[118:119], 0, vcc
	v_lshl_add_u64 v[120:121], v[120:121], 0, vcc
	v_lshl_add_u64 v[218:219], v[52:53], 0, v[116:117]
	global_load_dwordx4 v[66:69], v[218:219], off
	global_load_dwordx4 v[70:73], v[218:219], off offset:16
	global_load_dwordx4 v[74:77], v[218:219], off offset:2048
	global_load_dwordx4 v[78:81], v[218:219], off offset:2064
	global_load_dwordx4 v[82:85], v[118:119], off
	global_load_dwordx4 v[86:89], v[118:119], off offset:16
	global_load_dwordx4 v[90:93], v[118:119], off offset:2048
	global_load_dwordx4 v[94:97], v[118:119], off offset:2064
	global_load_dwordx4 v[98:101], v[120:121], off
	global_load_dwordx4 v[102:105], v[120:121], off offset:16
	global_load_dwordx4 v[106:109], v[120:121], off offset:2048
	global_load_dwordx4 v[110:113], v[120:121], off offset:2064
	s_mov_b32 vcc_lo, s25
	s_mov_b32 vcc_hi, 0
	s_lshl_b64 vcc, vcc, 11
	v_lshl_add_u64 v[118:119], v[54:55], 0, v[114:115]
	v_lshl_add_u64 v[118:119], v[118:119], 0, vcc
	global_load_dwordx4 v[122:125], v[118:119], off
	global_load_dwordx4 v[126:129], v[118:119], off offset:1024
	s_mov_b32 vcc_lo, s17
	s_mov_b32 vcc_hi, 0
	s_lshl_b64 vcc, vcc, 11
	v_lshl_add_u64 v[120:121], v[58:59], 0, v[114:115]
	v_lshl_add_u64 v[120:121], v[120:121], 0, vcc
	s_mov_b64 vcc, 0x200000
	global_load_dwordx4 v[130:133], v[120:121], off nt
	global_load_dwordx4 v[134:137], v[120:121], off offset:1024 nt
	v_lshl_add_u64 v[120:121], v[120:121], 0, vcc
	global_load_dwordx4 v[138:141], v[120:121], off nt
	global_load_dwordx4 v[142:145], v[120:121], off offset:1024 nt
	v_lshl_add_u64 v[120:121], v[120:121], 0, vcc
	global_load_dwordx4 v[146:149], v[120:121], off nt
	global_load_dwordx4 v[150:153], v[120:121], off offset:1024 nt
	v_lshl_add_u64 v[120:121], v[120:121], 0, vcc
	global_load_dwordx4 v[154:157], v[120:121], off nt
	global_load_dwordx4 v[158:161], v[120:121], off offset:1024 nt
	v_mov_b32_e32 v220, 0x3a800000
	v_mov_b32_e32 v221, 0x358637bd
	s_waitcnt vmcnt(10)
	v_pk_add_f32 v[82:83], v[82:83], 1.0 op_sel_hi:[1,0]
	v_pk_add_f32 v[84:85], v[84:85], 1.0 op_sel_hi:[1,0]
	v_pk_add_f32 v[86:87], v[86:87], 1.0 op_sel_hi:[1,0]
	v_pk_add_f32 v[88:89], v[88:89], 1.0 op_sel_hi:[1,0]
	v_pk_add_f32 v[90:91], v[90:91], 1.0 op_sel_hi:[1,0]
	v_pk_add_f32 v[92:93], v[92:93], 1.0 op_sel_hi:[1,0]
	v_pk_add_f32 v[94:95], v[94:95], 1.0 op_sel_hi:[1,0]
	v_pk_add_f32 v[96:97], v[96:97], 1.0 op_sel_hi:[1,0]
	v_pk_mul_f32 v[66:67], v[66:67], v[82:83]
	v_pk_mul_f32 v[68:69], v[68:69], v[84:85]
	v_pk_mul_f32 v[70:71], v[70:71], v[86:87]
	v_pk_mul_f32 v[72:73], v[72:73], v[88:89]
	v_pk_mul_f32 v[74:75], v[74:75], v[90:91]
	v_pk_mul_f32 v[76:77], v[76:77], v[92:93]
	v_pk_mul_f32 v[78:79], v[78:79], v[94:95]
	v_pk_mul_f32 v[80:81], v[80:81], v[96:97]
	s_waitcnt vmcnt(8)
	v_lshlrev_b32_e32 v82, 16, v122
	v_and_b32_e32 v83, 0xffff0000, v122
	v_lshlrev_b32_e32 v84, 16, v123
	v_and_b32_e32 v85, 0xffff0000, v123
	v_lshlrev_b32_e32 v86, 16, v124
	v_and_b32_e32 v87, 0xffff0000, v124
	v_lshlrev_b32_e32 v88, 16, v125
	v_and_b32_e32 v89, 0xffff0000, v125
	v_lshlrev_b32_e32 v90, 16, v126
	v_and_b32_e32 v91, 0xffff0000, v126
	v_lshlrev_b32_e32 v92, 16, v127
	v_and_b32_e32 v93, 0xffff0000, v127
	v_lshlrev_b32_e32 v94, 16, v128
	v_and_b32_e32 v95, 0xffff0000, v128
	v_lshlrev_b32_e32 v96, 16, v129
	v_and_b32_e32 v97, 0xffff0000, v129
	s_waitcnt vmcnt(6)
	v_lshlrev_b32_e32 v218, 16, v130
	v_and_b32_e32 v219, 0xffff0000, v130
	v_pk_add_f32 v[82:83], v[82:83], v[218:219]
	v_lshlrev_b32_e32 v218, 16, v131
	v_and_b32_e32 v219, 0xffff0000, v131
	v_pk_add_f32 v[84:85], v[84:85], v[218:219]
	v_lshlrev_b32_e32 v218, 16, v132
	v_and_b32_e32 v219, 0xffff0000, v132
	v_pk_add_f32 v[86:87], v[86:87], v[218:219]
	v_lshlrev_b32_e32 v218, 16, v133
	v_and_b32_e32 v219, 0xffff0000, v133
	v_pk_add_f32 v[88:89], v[88:89], v[218:219]
	v_lshlrev_b32_e32 v218, 16, v134
	v_and_b32_e32 v219, 0xffff0000, v134
	v_pk_add_f32 v[90:91], v[90:91], v[218:219]
	v_lshlrev_b32_e32 v218, 16, v135
	v_and_b32_e32 v219, 0xffff0000, v135
	v_pk_add_f32 v[92:93], v[92:93], v[218:219]
	v_lshlrev_b32_e32 v218, 16, v136
	v_and_b32_e32 v219, 0xffff0000, v136
	v_pk_add_f32 v[94:95], v[94:95], v[218:219]
	v_lshlrev_b32_e32 v218, 16, v137
	v_and_b32_e32 v219, 0xffff0000, v137
	v_pk_add_f32 v[96:97], v[96:97], v[218:219]
	s_waitcnt vmcnt(4)
	v_lshlrev_b32_e32 v218, 16, v138
	v_and_b32_e32 v219, 0xffff0000, v138
	v_pk_add_f32 v[82:83], v[82:83], v[218:219]
	v_lshlrev_b32_e32 v218, 16, v139
	v_and_b32_e32 v219, 0xffff0000, v139
	v_pk_add_f32 v[84:85], v[84:85], v[218:219]
	v_lshlrev_b32_e32 v218, 16, v140
	v_and_b32_e32 v219, 0xffff0000, v140
	v_pk_add_f32 v[86:87], v[86:87], v[218:219]
	v_lshlrev_b32_e32 v218, 16, v141
	v_and_b32_e32 v219, 0xffff0000, v141
	v_pk_add_f32 v[88:89], v[88:89], v[218:219]
	v_lshlrev_b32_e32 v218, 16, v142
	v_and_b32_e32 v219, 0xffff0000, v142
	v_pk_add_f32 v[90:91], v[90:91], v[218:219]
	v_lshlrev_b32_e32 v218, 16, v143
	v_and_b32_e32 v219, 0xffff0000, v143
	v_pk_add_f32 v[92:93], v[92:93], v[218:219]
	v_lshlrev_b32_e32 v218, 16, v144
	v_and_b32_e32 v219, 0xffff0000, v144
	v_pk_add_f32 v[94:95], v[94:95], v[218:219]
	v_lshlrev_b32_e32 v218, 16, v145
	v_and_b32_e32 v219, 0xffff0000, v145
	v_pk_add_f32 v[96:97], v[96:97], v[218:219]
	s_waitcnt vmcnt(2)
	v_lshlrev_b32_e32 v218, 16, v146
	v_and_b32_e32 v219, 0xffff0000, v146
	v_pk_add_f32 v[82:83], v[82:83], v[218:219]
	v_lshlrev_b32_e32 v218, 16, v147
	v_and_b32_e32 v219, 0xffff0000, v147
	v_pk_add_f32 v[84:85], v[84:85], v[218:219]
	v_lshlrev_b32_e32 v218, 16, v148
	v_and_b32_e32 v219, 0xffff0000, v148
	v_pk_add_f32 v[86:87], v[86:87], v[218:219]
	v_lshlrev_b32_e32 v218, 16, v149
	v_and_b32_e32 v219, 0xffff0000, v149
	v_pk_add_f32 v[88:89], v[88:89], v[218:219]
	v_lshlrev_b32_e32 v218, 16, v150
	v_and_b32_e32 v219, 0xffff0000, v150
	v_pk_add_f32 v[90:91], v[90:91], v[218:219]
	v_lshlrev_b32_e32 v218, 16, v151
	v_and_b32_e32 v219, 0xffff0000, v151
	v_pk_add_f32 v[92:93], v[92:93], v[218:219]
	v_lshlrev_b32_e32 v218, 16, v152
	v_and_b32_e32 v219, 0xffff0000, v152
	v_pk_add_f32 v[94:95], v[94:95], v[218:219]
	v_lshlrev_b32_e32 v218, 16, v153
	v_and_b32_e32 v219, 0xffff0000, v153
	v_pk_add_f32 v[96:97], v[96:97], v[218:219]
	s_waitcnt vmcnt(0)
	v_lshlrev_b32_e32 v218, 16, v154
	v_and_b32_e32 v219, 0xffff0000, v154
	v_pk_add_f32 v[82:83], v[82:83], v[218:219]
	v_lshlrev_b32_e32 v218, 16, v155
	v_and_b32_e32 v219, 0xffff0000, v155
	v_pk_add_f32 v[84:85], v[84:85], v[218:219]
	v_lshlrev_b32_e32 v218, 16, v156
	v_and_b32_e32 v219, 0xffff0000, v156
	v_pk_add_f32 v[86:87], v[86:87], v[218:219]
	v_lshlrev_b32_e32 v218, 16, v157
	v_and_b32_e32 v219, 0xffff0000, v157
	v_pk_add_f32 v[88:89], v[88:89], v[218:219]
	v_lshlrev_b32_e32 v218, 16, v158
	v_and_b32_e32 v219, 0xffff0000, v158
	v_pk_add_f32 v[90:91], v[90:91], v[218:219]
	v_lshlrev_b32_e32 v218, 16, v159
	v_and_b32_e32 v219, 0xffff0000, v159
	v_pk_add_f32 v[92:93], v[92:93], v[218:219]
	v_lshlrev_b32_e32 v218, 16, v160
	v_and_b32_e32 v219, 0xffff0000, v160
	v_pk_add_f32 v[94:95], v[94:95], v[218:219]
	v_lshlrev_b32_e32 v218, 16, v161
	v_and_b32_e32 v219, 0xffff0000, v161
	v_pk_add_f32 v[96:97], v[96:97], v[218:219]
	v_cvt_pk_bf16_f32 v122, v82, v83
	v_cvt_pk_bf16_f32 v123, v84, v85
	v_cvt_pk_bf16_f32 v124, v86, v87
	v_cvt_pk_bf16_f32 v125, v88, v89
	v_cvt_pk_bf16_f32 v126, v90, v91
	v_cvt_pk_bf16_f32 v127, v92, v93
	v_cvt_pk_bf16_f32 v128, v94, v95
	v_cvt_pk_bf16_f32 v129, v96, v97
	global_store_dwordx4 v[118:119], v[122:125], off sc1
	global_store_dwordx4 v[118:119], v[126:129], off offset:1024 sc1
	v_mul_f32_e32 v218, v82, v82
	v_mul_f32_e32 v219, v83, v83
	v_fmac_f32_e32 v218, v84, v84
	v_fmac_f32_e32 v219, v85, v85
	v_fmac_f32_e32 v218, v86, v86
	v_fmac_f32_e32 v219, v87, v87
	v_fmac_f32_e32 v218, v88, v88
	v_fmac_f32_e32 v219, v89, v89
	v_fmac_f32_e32 v218, v90, v90
	v_fmac_f32_e32 v219, v91, v91
	v_fmac_f32_e32 v218, v92, v92
	v_fmac_f32_e32 v219, v93, v93
	v_fmac_f32_e32 v218, v94, v94
	v_fmac_f32_e32 v219, v95, v95
	v_fmac_f32_e32 v218, v96, v96
	v_fmac_f32_e32 v219, v97, v97
	v_add_f32_e32 v218, v218, v219
	s_nop 1
	v_add_f32_dpp v218, v218, v218 quad_perm:[1,0,3,2] row_mask:0xf bank_mask:0xf
	s_nop 1
	v_add_f32_dpp v218, v218, v218 quad_perm:[2,3,0,1] row_mask:0xf bank_mask:0xf
	s_nop 1
	v_add_f32_dpp v218, v218, v218 row_half_mirror row_mask:0xf bank_mask:0xf
	s_nop 1
	v_add_f32_dpp v218, v218, v218 row_mirror row_mask:0xf bank_mask:0xf
	s_nop 1
	v_add_f32_dpp v218, v218, v218 row_bcast:15 row_mask:0xa bank_mask:0xf
	s_nop 1
	v_add_f32_dpp v218, v218, v218 row_bcast:31 row_mask:0xc bank_mask:0xf
	s_nop 1
	v_readlane_b32 vcc_lo, v218, 63
	s_nop 2
	v_fma_f32 v222, vcc_lo, v220, v221
	v_rsq_f32_e32 v222, v222
	s_mov_b64 vcc, 0x4400000
	v_lshl_add_u64 v[118:119], v[118:119], 0, vcc
	v_pk_mul_f32 v[82:83], v[82:83], v[222:223] op_sel_hi:[1,0]
	v_pk_fma_f32 v[82:83], v[82:83], v[66:67], v[98:99]
	v_pk_mul_f32 v[84:85], v[84:85], v[222:223] op_sel_hi:[1,0]
	v_pk_fma_f32 v[84:85], v[84:85], v[68:69], v[100:101]
	v_pk_mul_f32 v[86:87], v[86:87], v[222:223] op_sel_hi:[1,0]
	v_pk_fma_f32 v[86:87], v[86:87], v[70:71], v[102:103]
	v_pk_mul_f32 v[88:89], v[88:89], v[222:223] op_sel_hi:[1,0]
	v_pk_fma_f32 v[88:89], v[88:89], v[72:73], v[104:105]
	v_pk_mul_f32 v[90:91], v[90:91], v[222:223] op_sel_hi:[1,0]
	v_pk_fma_f32 v[90:91], v[90:91], v[74:75], v[106:107]
	v_pk_mul_f32 v[92:93], v[92:93], v[222:223] op_sel_hi:[1,0]
	v_pk_fma_f32 v[92:93], v[92:93], v[76:77], v[108:109]
	v_pk_mul_f32 v[94:95], v[94:95], v[222:223] op_sel_hi:[1,0]
	v_pk_fma_f32 v[94:95], v[94:95], v[78:79], v[110:111]
	v_pk_mul_f32 v[96:97], v[96:97], v[222:223] op_sel_hi:[1,0]
	v_pk_fma_f32 v[96:97], v[96:97], v[80:81], v[112:113]
	v_cvt_pk_bf16_f32 v66, v82, v83
	v_cvt_pk_bf16_f32 v67, v84, v85
	v_cvt_pk_bf16_f32 v68, v86, v87
	v_cvt_pk_bf16_f32 v69, v88, v89
	v_cvt_pk_bf16_f32 v70, v90, v91
	v_cvt_pk_bf16_f32 v71, v92, v93
	v_cvt_pk_bf16_f32 v72, v94, v95
	v_cvt_pk_bf16_f32 v73, v96, v97
	global_store_dwordx4 v[118:119], v[66:69], off sc1
	global_store_dwordx4 v[118:119], v[70:73], off offset:1024 sc1
	s_branch .Lnc_done
.Lnc_11:
	s_mov_b64 vcc, 0x24000
	v_lshl_add_u64 v[118:119], v[62:63], 0, v[116:117]
	v_lshl_add_u64 v[120:121], v[60:61], 0, v[116:117]
	v_lshl_add_u64 v[118:119], v[118:119], 0, vcc
	v_lshl_add_u64 v[120:121], v[120:121], 0, vcc
	v_lshl_add_u64 v[218:219], v[52:53], 0, v[116:117]
	global_load_dwordx4 v[66:69], v[218:219], off
	global_load_dwordx4 v[70:73], v[218:219], off offset:16
	global_load_dwordx4 v[74:77], v[218:219], off offset:2048
	global_load_dwordx4 v[78:81], v[218:219], off offset:2064
	global_load_dwordx4 v[82:85], v[118:119], off
	global_load_dwordx4 v[86:89], v[118:119], off offset:16
	global_load_dwordx4 v[90:93], v[118:119], off offset:2048
	global_load_dwordx4 v[94:97], v[118:119], off offset:2064
	global_load_dwordx4 v[98:101], v[120:121], off
	global_load_dwordx4 v[102:105], v[120:121], off offset:16
	global_load_dwordx4 v[106:109], v[120:121], off offset:2048
	global_load_dwordx4 v[110:113], v[120:121], off offset:2064
	s_mov_b32 vcc_lo, s25
	s_mov_b32 vcc_hi, 0
	s_lshl_b64 vcc, vcc, 11
	v_lshl_add_u64 v[118:119], v[54:55], 0, v[114:115]
	v_lshl_add_u64 v[118:119], v[118:119], 0, vcc
	global_load_dwordx4 v[122:125], v[118:119], off
	global_load_dwordx4 v[126:129], v[118:119], off offset:1024
	s_mov_b32 vcc_lo, s17
	s_mov_b32 vcc_hi, 0
	s_lshl_b64 vcc, vcc, 11
	v_lshl_add_u64 v[120:121], v[58:59], 0, v[114:115]
	v_lshl_add_u64 v[120:121], v[120:121], 0, vcc
	s_mov_b64 vcc, 0x200000
	global_load_dwordx4 v[130:133], v[120:121], off nt
	global_load_dwordx4 v[134:137], v[120:121], off offset:1024 nt
	v_lshl_add_u64 v[120:121], v[120:121], 0, vcc
	global_load_dwordx4 v[138:141], v[120:121], off nt
	global_load_dwordx4 v[142:145], v[120:121], off offset:1024 nt
	v_lshl_add_u64 v[120:121], v[120:121], 0, vcc
	global_load_dwordx4 v[146:149], v[120:121], off nt
	global_load_dwordx4 v[150:153], v[120:121], off offset:1024 nt
	v_lshl_add_u64 v[120:121], v[120:121], 0, vcc
	global_load_dwordx4 v[154:157], v[120:121], off nt
	global_load_dwordx4 v[158:161], v[120:121], off offset:1024 nt
	v_lshl_add_u64 v[120:121], v[120:121], 0, vcc
	global_load_dwordx4 v[162:165], v[120:121], off nt
	global_load_dwordx4 v[166:169], v[120:121], off offset:1024 nt
	v_lshl_add_u64 v[120:121], v[120:121], 0, vcc
	global_load_dwordx4 v[170:173], v[120:121], off nt
	global_load_dwordx4 v[174:177], v[120:121], off offset:1024 nt
	v_lshl_add_u64 v[120:121], v[120:121], 0, vcc
	global_load_dwordx4 v[178:181], v[120:121], off nt
	global_load_dwordx4 v[182:185], v[120:121], off offset:1024 nt
	v_lshl_add_u64 v[120:121], v[120:121], 0, vcc
	global_load_dwordx4 v[186:189], v[120:121], off nt
	global_load_dwordx4 v[190:193], v[120:121], off offset:1024 nt
	v_lshl_add_u64 v[120:121], v[120:121], 0, vcc
	global_load_dwordx4 v[194:197], v[120:121], off nt
	global_load_dwordx4 v[198:201], v[120:121], off offset:1024 nt
	v_lshl_add_u64 v[120:121], v[120:121], 0, vcc
	global_load_dwordx4 v[202:205], v[120:121], off nt
	global_load_dwordx4 v[206:209], v[120:121], off offset:1024 nt
	v_lshl_add_u64 v[120:121], v[120:121], 0, vcc
	global_load_dwordx4 v[210:213], v[120:121], off nt
	global_load_dwordx4 v[214:217], v[120:121], off offset:1024 nt
	v_mov_b32_e32 v220, 0x3a800000
	v_mov_b32_e32 v221, 0x358637bd
	s_waitcnt vmcnt(24)
	v_pk_add_f32 v[82:83], v[82:83], 1.0 op_sel_hi:[1,0]
	v_pk_add_f32 v[84:85], v[84:85], 1.0 op_sel_hi:[1,0]
	v_pk_add_f32 v[86:87], v[86:87], 1.0 op_sel_hi:[1,0]
	v_pk_add_f32 v[88:89], v[88:89], 1.0 op_sel_hi:[1,0]
	v_pk_add_f32 v[90:91], v[90:91], 1.0 op_sel_hi:[1,0]
	v_pk_add_f32 v[92:93], v[92:93], 1.0 op_sel_hi:[1,0]
	v_pk_add_f32 v[94:95], v[94:95], 1.0 op_sel_hi:[1,0]
	v_pk_add_f32 v[96:97], v[96:97], 1.0 op_sel_hi:[1,0]
	v_pk_mul_f32 v[66:67], v[66:67], v[82:83]
	v_pk_mul_f32 v[68:69], v[68:69], v[84:85]
	v_pk_mul_f32 v[70:71], v[70:71], v[86:87]
	v_pk_mul_f32 v[72:73], v[72:73], v[88:89]
	v_pk_mul_f32 v[74:75], v[74:75], v[90:91]
	v_pk_mul_f32 v[76:77], v[76:77], v[92:93]
	v_pk_mul_f32 v[78:79], v[78:79], v[94:95]
	v_pk_mul_f32 v[80:81], v[80:81], v[96:97]
	s_waitcnt vmcnt(22)
	v_lshlrev_b32_e32 v82, 16, v122
	v_and_b32_e32 v83, 0xffff0000, v122
	v_lshlrev_b32_e32 v84, 16, v123
	v_and_b32_e32 v85, 0xffff0000, v123
	v_lshlrev_b32_e32 v86, 16, v124
	v_and_b32_e32 v87, 0xffff0000, v124
	v_lshlrev_b32_e32 v88, 16, v125
	v_and_b32_e32 v89, 0xffff0000, v125
	v_lshlrev_b32_e32 v90, 16, v126
	v_and_b32_e32 v91, 0xffff0000, v126
	v_lshlrev_b32_e32 v92, 16, v127
	v_and_b32_e32 v93, 0xffff0000, v127
	v_lshlrev_b32_e32 v94, 16, v128
	v_and_b32_e32 v95, 0xffff0000, v128
	v_lshlrev_b32_e32 v96, 16, v129
	v_and_b32_e32 v97, 0xffff0000, v129
	s_waitcnt vmcnt(20)
	v_lshlrev_b32_e32 v218, 16, v130
	v_and_b32_e32 v219, 0xffff0000, v130
	v_pk_add_f32 v[82:83], v[82:83], v[218:219]
	v_lshlrev_b32_e32 v218, 16, v131
	v_and_b32_e32 v219, 0xffff0000, v131
	v_pk_add_f32 v[84:85], v[84:85], v[218:219]
	v_lshlrev_b32_e32 v218, 16, v132
	v_and_b32_e32 v219, 0xffff0000, v132
	v_pk_add_f32 v[86:87], v[86:87], v[218:219]
	v_lshlrev_b32_e32 v218, 16, v133
	v_and_b32_e32 v219, 0xffff0000, v133
	v_pk_add_f32 v[88:89], v[88:89], v[218:219]
	v_lshlrev_b32_e32 v218, 16, v134
	v_and_b32_e32 v219, 0xffff0000, v134
	v_pk_add_f32 v[90:91], v[90:91], v[218:219]
	v_lshlrev_b32_e32 v218, 16, v135
	v_and_b32_e32 v219, 0xffff0000, v135
	v_pk_add_f32 v[92:93], v[92:93], v[218:219]
	v_lshlrev_b32_e32 v218, 16, v136
	v_and_b32_e32 v219, 0xffff0000, v136
	v_pk_add_f32 v[94:95], v[94:95], v[218:219]
	v_lshlrev_b32_e32 v218, 16, v137
	v_and_b32_e32 v219, 0xffff0000, v137
	v_pk_add_f32 v[96:97], v[96:97], v[218:219]
	s_waitcnt vmcnt(18)
	v_lshlrev_b32_e32 v218, 16, v138
	v_and_b32_e32 v219, 0xffff0000, v138
	v_pk_add_f32 v[82:83], v[82:83], v[218:219]
	v_lshlrev_b32_e32 v218, 16, v139
	v_and_b32_e32 v219, 0xffff0000, v139
	v_pk_add_f32 v[84:85], v[84:85], v[218:219]
	v_lshlrev_b32_e32 v218, 16, v140
	v_and_b32_e32 v219, 0xffff0000, v140
	v_pk_add_f32 v[86:87], v[86:87], v[218:219]
	v_lshlrev_b32_e32 v218, 16, v141
	v_and_b32_e32 v219, 0xffff0000, v141
	v_pk_add_f32 v[88:89], v[88:89], v[218:219]
	v_lshlrev_b32_e32 v218, 16, v142
	v_and_b32_e32 v219, 0xffff0000, v142
	v_pk_add_f32 v[90:91], v[90:91], v[218:219]
	v_lshlrev_b32_e32 v218, 16, v143
	v_and_b32_e32 v219, 0xffff0000, v143
	v_pk_add_f32 v[92:93], v[92:93], v[218:219]
	v_lshlrev_b32_e32 v218, 16, v144
	v_and_b32_e32 v219, 0xffff0000, v144
	v_pk_add_f32 v[94:95], v[94:95], v[218:219]
	v_lshlrev_b32_e32 v218, 16, v145
	v_and_b32_e32 v219, 0xffff0000, v145
	v_pk_add_f32 v[96:97], v[96:97], v[218:219]
	s_waitcnt vmcnt(16)
	v_lshlrev_b32_e32 v218, 16, v146
	v_and_b32_e32 v219, 0xffff0000, v146
	v_pk_add_f32 v[82:83], v[82:83], v[218:219]
	v_lshlrev_b32_e32 v218, 16, v147
	v_and_b32_e32 v219, 0xffff0000, v147
	v_pk_add_f32 v[84:85], v[84:85], v[218:219]
	v_lshlrev_b32_e32 v218, 16, v148
	v_and_b32_e32 v219, 0xffff0000, v148
	v_pk_add_f32 v[86:87], v[86:87], v[218:219]
	v_lshlrev_b32_e32 v218, 16, v149
	v_and_b32_e32 v219, 0xffff0000, v149
	v_pk_add_f32 v[88:89], v[88:89], v[218:219]
	v_lshlrev_b32_e32 v218, 16, v150
	v_and_b32_e32 v219, 0xffff0000, v150
	v_pk_add_f32 v[90:91], v[90:91], v[218:219]
	v_lshlrev_b32_e32 v218, 16, v151
	v_and_b32_e32 v219, 0xffff0000, v151
	v_pk_add_f32 v[92:93], v[92:93], v[218:219]
	v_lshlrev_b32_e32 v218, 16, v152
	v_and_b32_e32 v219, 0xffff0000, v152
	v_pk_add_f32 v[94:95], v[94:95], v[218:219]
	v_lshlrev_b32_e32 v218, 16, v153
	v_and_b32_e32 v219, 0xffff0000, v153
	v_pk_add_f32 v[96:97], v[96:97], v[218:219]
	s_waitcnt vmcnt(14)
	v_lshlrev_b32_e32 v218, 16, v154
	v_and_b32_e32 v219, 0xffff0000, v154
	v_pk_add_f32 v[82:83], v[82:83], v[218:219]
	v_lshlrev_b32_e32 v218, 16, v155
	v_and_b32_e32 v219, 0xffff0000, v155
	v_pk_add_f32 v[84:85], v[84:85], v[218:219]
	v_lshlrev_b32_e32 v218, 16, v156
	v_and_b32_e32 v219, 0xffff0000, v156
	v_pk_add_f32 v[86:87], v[86:87], v[218:219]
	v_lshlrev_b32_e32 v218, 16, v157
	v_and_b32_e32 v219, 0xffff0000, v157
	v_pk_add_f32 v[88:89], v[88:89], v[218:219]
	v_lshlrev_b32_e32 v218, 16, v158
	v_and_b32_e32 v219, 0xffff0000, v158
	v_pk_add_f32 v[90:91], v[90:91], v[218:219]
	v_lshlrev_b32_e32 v218, 16, v159
	v_and_b32_e32 v219, 0xffff0000, v159
	v_pk_add_f32 v[92:93], v[92:93], v[218:219]
	v_lshlrev_b32_e32 v218, 16, v160
	v_and_b32_e32 v219, 0xffff0000, v160
	v_pk_add_f32 v[94:95], v[94:95], v[218:219]
	v_lshlrev_b32_e32 v218, 16, v161
	v_and_b32_e32 v219, 0xffff0000, v161
	v_pk_add_f32 v[96:97], v[96:97], v[218:219]
	s_waitcnt vmcnt(12)
	v_lshlrev_b32_e32 v218, 16, v162
	v_and_b32_e32 v219, 0xffff0000, v162
	v_pk_add_f32 v[82:83], v[82:83], v[218:219]
	v_lshlrev_b32_e32 v218, 16, v163
	v_and_b32_e32 v219, 0xffff0000, v163
	v_pk_add_f32 v[84:85], v[84:85], v[218:219]
	v_lshlrev_b32_e32 v218, 16, v164
	v_and_b32_e32 v219, 0xffff0000, v164
	v_pk_add_f32 v[86:87], v[86:87], v[218:219]
	v_lshlrev_b32_e32 v218, 16, v165
	v_and_b32_e32 v219, 0xffff0000, v165
	v_pk_add_f32 v[88:89], v[88:89], v[218:219]
	v_lshlrev_b32_e32 v218, 16, v166
	v_and_b32_e32 v219, 0xffff0000, v166
	v_pk_add_f32 v[90:91], v[90:91], v[218:219]
	v_lshlrev_b32_e32 v218, 16, v167
	v_and_b32_e32 v219, 0xffff0000, v167
	v_pk_add_f32 v[92:93], v[92:93], v[218:219]
	v_lshlrev_b32_e32 v218, 16, v168
	v_and_b32_e32 v219, 0xffff0000, v168
	v_pk_add_f32 v[94:95], v[94:95], v[218:219]
	v_lshlrev_b32_e32 v218, 16, v169
	v_and_b32_e32 v219, 0xffff0000, v169
	v_pk_add_f32 v[96:97], v[96:97], v[218:219]
	s_waitcnt vmcnt(10)
	v_lshlrev_b32_e32 v218, 16, v170
	v_and_b32_e32 v219, 0xffff0000, v170
	v_pk_add_f32 v[82:83], v[82:83], v[218:219]
	v_lshlrev_b32_e32 v218, 16, v171
	v_and_b32_e32 v219, 0xffff0000, v171
	v_pk_add_f32 v[84:85], v[84:85], v[218:219]
	v_lshlrev_b32_e32 v218, 16, v172
	v_and_b32_e32 v219, 0xffff0000, v172
	v_pk_add_f32 v[86:87], v[86:87], v[218:219]
	v_lshlrev_b32_e32 v218, 16, v173
	v_and_b32_e32 v219, 0xffff0000, v173
	v_pk_add_f32 v[88:89], v[88:89], v[218:219]
	v_lshlrev_b32_e32 v218, 16, v174
	v_and_b32_e32 v219, 0xffff0000, v174
	v_pk_add_f32 v[90:91], v[90:91], v[218:219]
	v_lshlrev_b32_e32 v218, 16, v175
	v_and_b32_e32 v219, 0xffff0000, v175
	v_pk_add_f32 v[92:93], v[92:93], v[218:219]
	v_lshlrev_b32_e32 v218, 16, v176
	v_and_b32_e32 v219, 0xffff0000, v176
	v_pk_add_f32 v[94:95], v[94:95], v[218:219]
	v_lshlrev_b32_e32 v218, 16, v177
	v_and_b32_e32 v219, 0xffff0000, v177
	v_pk_add_f32 v[96:97], v[96:97], v[218:219]
	s_waitcnt vmcnt(8)
	v_lshlrev_b32_e32 v218, 16, v178
	v_and_b32_e32 v219, 0xffff0000, v178
	v_pk_add_f32 v[82:83], v[82:83], v[218:219]
	v_lshlrev_b32_e32 v218, 16, v179
	v_and_b32_e32 v219, 0xffff0000, v179
	v_pk_add_f32 v[84:85], v[84:85], v[218:219]
	v_lshlrev_b32_e32 v218, 16, v180
	v_and_b32_e32 v219, 0xffff0000, v180
	v_pk_add_f32 v[86:87], v[86:87], v[218:219]
	v_lshlrev_b32_e32 v218, 16, v181
	v_and_b32_e32 v219, 0xffff0000, v181
	v_pk_add_f32 v[88:89], v[88:89], v[218:219]
	v_lshlrev_b32_e32 v218, 16, v182
	v_and_b32_e32 v219, 0xffff0000, v182
	v_pk_add_f32 v[90:91], v[90:91], v[218:219]
	v_lshlrev_b32_e32 v218, 16, v183
	v_and_b32_e32 v219, 0xffff0000, v183
	v_pk_add_f32 v[92:93], v[92:93], v[218:219]
	v_lshlrev_b32_e32 v218, 16, v184
	v_and_b32_e32 v219, 0xffff0000, v184
	v_pk_add_f32 v[94:95], v[94:95], v[218:219]
	v_lshlrev_b32_e32 v218, 16, v185
	v_and_b32_e32 v219, 0xffff0000, v185
	v_pk_add_f32 v[96:97], v[96:97], v[218:219]
	s_waitcnt vmcnt(6)
	v_lshlrev_b32_e32 v218, 16, v186
	v_and_b32_e32 v219, 0xffff0000, v186
	v_pk_add_f32 v[82:83], v[82:83], v[218:219]
	v_lshlrev_b32_e32 v218, 16, v187
	v_and_b32_e32 v219, 0xffff0000, v187
	v_pk_add_f32 v[84:85], v[84:85], v[218:219]
	v_lshlrev_b32_e32 v218, 16, v188
	v_and_b32_e32 v219, 0xffff0000, v188
	v_pk_add_f32 v[86:87], v[86:87], v[218:219]
	v_lshlrev_b32_e32 v218, 16, v189
	v_and_b32_e32 v219, 0xffff0000, v189
	v_pk_add_f32 v[88:89], v[88:89], v[218:219]
	v_lshlrev_b32_e32 v218, 16, v190
	v_and_b32_e32 v219, 0xffff0000, v190
	v_pk_add_f32 v[90:91], v[90:91], v[218:219]
	v_lshlrev_b32_e32 v218, 16, v191
	v_and_b32_e32 v219, 0xffff0000, v191
	v_pk_add_f32 v[92:93], v[92:93], v[218:219]
	v_lshlrev_b32_e32 v218, 16, v192
	v_and_b32_e32 v219, 0xffff0000, v192
	v_pk_add_f32 v[94:95], v[94:95], v[218:219]
	v_lshlrev_b32_e32 v218, 16, v193
	v_and_b32_e32 v219, 0xffff0000, v193
	v_pk_add_f32 v[96:97], v[96:97], v[218:219]
	s_waitcnt vmcnt(4)
	v_lshlrev_b32_e32 v218, 16, v194
	v_and_b32_e32 v219, 0xffff0000, v194
	v_pk_add_f32 v[82:83], v[82:83], v[218:219]
	v_lshlrev_b32_e32 v218, 16, v195
	v_and_b32_e32 v219, 0xffff0000, v195
	v_pk_add_f32 v[84:85], v[84:85], v[218:219]
	v_lshlrev_b32_e32 v218, 16, v196
	v_and_b32_e32 v219, 0xffff0000, v196
	v_pk_add_f32 v[86:87], v[86:87], v[218:219]
	v_lshlrev_b32_e32 v218, 16, v197
	v_and_b32_e32 v219, 0xffff0000, v197
	v_pk_add_f32 v[88:89], v[88:89], v[218:219]
	v_lshlrev_b32_e32 v218, 16, v198
	v_and_b32_e32 v219, 0xffff0000, v198
	v_pk_add_f32 v[90:91], v[90:91], v[218:219]
	v_lshlrev_b32_e32 v218, 16, v199
	v_and_b32_e32 v219, 0xffff0000, v199
	v_pk_add_f32 v[92:93], v[92:93], v[218:219]
	v_lshlrev_b32_e32 v218, 16, v200
	v_and_b32_e32 v219, 0xffff0000, v200
	v_pk_add_f32 v[94:95], v[94:95], v[218:219]
	v_lshlrev_b32_e32 v218, 16, v201
	v_and_b32_e32 v219, 0xffff0000, v201
	v_pk_add_f32 v[96:97], v[96:97], v[218:219]
	s_waitcnt vmcnt(2)
	v_lshlrev_b32_e32 v218, 16, v202
	v_and_b32_e32 v219, 0xffff0000, v202
	v_pk_add_f32 v[82:83], v[82:83], v[218:219]
	v_lshlrev_b32_e32 v218, 16, v203
	v_and_b32_e32 v219, 0xffff0000, v203
	v_pk_add_f32 v[84:85], v[84:85], v[218:219]
	v_lshlrev_b32_e32 v218, 16, v204
	v_and_b32_e32 v219, 0xffff0000, v204
	v_pk_add_f32 v[86:87], v[86:87], v[218:219]
	v_lshlrev_b32_e32 v218, 16, v205
	v_and_b32_e32 v219, 0xffff0000, v205
	v_pk_add_f32 v[88:89], v[88:89], v[218:219]
	v_lshlrev_b32_e32 v218, 16, v206
	v_and_b32_e32 v219, 0xffff0000, v206
	v_pk_add_f32 v[90:91], v[90:91], v[218:219]
	v_lshlrev_b32_e32 v218, 16, v207
	v_and_b32_e32 v219, 0xffff0000, v207
	v_pk_add_f32 v[92:93], v[92:93], v[218:219]
	v_lshlrev_b32_e32 v218, 16, v208
	v_and_b32_e32 v219, 0xffff0000, v208
	v_pk_add_f32 v[94:95], v[94:95], v[218:219]
	v_lshlrev_b32_e32 v218, 16, v209
	v_and_b32_e32 v219, 0xffff0000, v209
	v_pk_add_f32 v[96:97], v[96:97], v[218:219]
	s_waitcnt vmcnt(0)
	v_lshlrev_b32_e32 v218, 16, v210
	v_and_b32_e32 v219, 0xffff0000, v210
	v_pk_add_f32 v[82:83], v[82:83], v[218:219]
	v_lshlrev_b32_e32 v218, 16, v211
	v_and_b32_e32 v219, 0xffff0000, v211
	v_pk_add_f32 v[84:85], v[84:85], v[218:219]
	v_lshlrev_b32_e32 v218, 16, v212
	v_and_b32_e32 v219, 0xffff0000, v212
	v_pk_add_f32 v[86:87], v[86:87], v[218:219]
	v_lshlrev_b32_e32 v218, 16, v213
	v_and_b32_e32 v219, 0xffff0000, v213
	v_pk_add_f32 v[88:89], v[88:89], v[218:219]
	v_lshlrev_b32_e32 v218, 16, v214
	v_and_b32_e32 v219, 0xffff0000, v214
	v_pk_add_f32 v[90:91], v[90:91], v[218:219]
	v_lshlrev_b32_e32 v218, 16, v215
	v_and_b32_e32 v219, 0xffff0000, v215
	v_pk_add_f32 v[92:93], v[92:93], v[218:219]
	v_lshlrev_b32_e32 v218, 16, v216
	v_and_b32_e32 v219, 0xffff0000, v216
	v_pk_add_f32 v[94:95], v[94:95], v[218:219]
	v_lshlrev_b32_e32 v218, 16, v217
	v_and_b32_e32 v219, 0xffff0000, v217
	v_pk_add_f32 v[96:97], v[96:97], v[218:219]
	v_cvt_pk_bf16_f32 v122, v82, v83
	v_cvt_pk_bf16_f32 v123, v84, v85
	v_cvt_pk_bf16_f32 v124, v86, v87
	v_cvt_pk_bf16_f32 v125, v88, v89
	v_cvt_pk_bf16_f32 v126, v90, v91
	v_cvt_pk_bf16_f32 v127, v92, v93
	v_cvt_pk_bf16_f32 v128, v94, v95
	v_cvt_pk_bf16_f32 v129, v96, v97
	global_store_dwordx4 v[118:119], v[122:125], off sc1
	global_store_dwordx4 v[118:119], v[126:129], off offset:1024 sc1
	v_mul_f32_e32 v218, v82, v82
	v_mul_f32_e32 v219, v83, v83
	v_fmac_f32_e32 v218, v84, v84
	v_fmac_f32_e32 v219, v85, v85
	v_fmac_f32_e32 v218, v86, v86
	v_fmac_f32_e32 v219, v87, v87
	v_fmac_f32_e32 v218, v88, v88
	v_fmac_f32_e32 v219, v89, v89
	v_fmac_f32_e32 v218, v90, v90
	v_fmac_f32_e32 v219, v91, v91
	v_fmac_f32_e32 v218, v92, v92
	v_fmac_f32_e32 v219, v93, v93
	v_fmac_f32_e32 v218, v94, v94
	v_fmac_f32_e32 v219, v95, v95
	v_fmac_f32_e32 v218, v96, v96
	v_fmac_f32_e32 v219, v97, v97
	v_add_f32_e32 v218, v218, v219
	s_nop 1
	v_add_f32_dpp v218, v218, v218 quad_perm:[1,0,3,2] row_mask:0xf bank_mask:0xf
	s_nop 1
	v_add_f32_dpp v218, v218, v218 quad_perm:[2,3,0,1] row_mask:0xf bank_mask:0xf
	s_nop 1
	v_add_f32_dpp v218, v218, v218 row_half_mirror row_mask:0xf bank_mask:0xf
	s_nop 1
	v_add_f32_dpp v218, v218, v218 row_mirror row_mask:0xf bank_mask:0xf
	s_nop 1
	v_add_f32_dpp v218, v218, v218 row_bcast:15 row_mask:0xa bank_mask:0xf
	s_nop 1
	v_add_f32_dpp v218, v218, v218 row_bcast:31 row_mask:0xc bank_mask:0xf
	s_nop 1
	v_readlane_b32 vcc_lo, v218, 63
	s_nop 2
	v_fma_f32 v222, vcc_lo, v220, v221
	v_rsq_f32_e32 v222, v222
	s_mov_b64 vcc, 0x4400000
	v_lshl_add_u64 v[118:119], v[118:119], 0, vcc
	v_pk_mul_f32 v[82:83], v[82:83], v[222:223] op_sel_hi:[1,0]
	v_pk_fma_f32 v[82:83], v[82:83], v[66:67], v[98:99]
	v_pk_mul_f32 v[84:85], v[84:85], v[222:223] op_sel_hi:[1,0]
	v_pk_fma_f32 v[84:85], v[84:85], v[68:69], v[100:101]
	v_pk_mul_f32 v[86:87], v[86:87], v[222:223] op_sel_hi:[1,0]
	v_pk_fma_f32 v[86:87], v[86:87], v[70:71], v[102:103]
	v_pk_mul_f32 v[88:89], v[88:89], v[222:223] op_sel_hi:[1,0]
	v_pk_fma_f32 v[88:89], v[88:89], v[72:73], v[104:105]
	v_pk_mul_f32 v[90:91], v[90:91], v[222:223] op_sel_hi:[1,0]
	v_pk_fma_f32 v[90:91], v[90:91], v[74:75], v[106:107]
	v_pk_mul_f32 v[92:93], v[92:93], v[222:223] op_sel_hi:[1,0]
	v_pk_fma_f32 v[92:93], v[92:93], v[76:77], v[108:109]
	v_pk_mul_f32 v[94:95], v[94:95], v[222:223] op_sel_hi:[1,0]
	v_pk_fma_f32 v[94:95], v[94:95], v[78:79], v[110:111]
	v_pk_mul_f32 v[96:97], v[96:97], v[222:223] op_sel_hi:[1,0]
	v_pk_fma_f32 v[96:97], v[96:97], v[80:81], v[112:113]
	v_cvt_pk_bf16_f32 v66, v82, v83
	v_cvt_pk_bf16_f32 v67, v84, v85
	v_cvt_pk_bf16_f32 v68, v86, v87
	v_cvt_pk_bf16_f32 v69, v88, v89
	v_cvt_pk_bf16_f32 v70, v90, v91
	v_cvt_pk_bf16_f32 v71, v92, v93
	v_cvt_pk_bf16_f32 v72, v94, v95
	v_cvt_pk_bf16_f32 v73, v96, v97
	global_store_dwordx4 v[118:119], v[66:69], off sc1
	global_store_dwordx4 v[118:119], v[70:73], off offset:1024 sc1
	s_branch .Lnc_done

.LBB0_637:
	s_andn2_saveexec_b64 s[6:7], s[6:7]
	s_cbranch_execz .LBB0_133
	s_mov_b64 s[6:7], exec
	s_bitcmp1_b32 0xd5b56, s3
	s_cbranch_scc1 .Lskip_wbl2
	s_bitcmp1_b32 0x22488, s3
	s_cbranch_scc0 .Ldo_wbl2
	s_cmpk_eq_i32 s21, 0x100
	s_cbranch_scc1 .Lskip_wbl2
.Ldo_wbl2:
	buffer_wbl2 sc1
